# K-loop MFMA order: the two k-step MFMAs of each accumulator back to back, chains sharing the first source operand adjacent
# speedup vs baseline: 1.0105x; 1.0022x over previous
; #define PG8_STAGE(bufoff, gbase, voff) do { const char* gb_ = (const char*)(gbase); asm volatile("" : "+s"(gb_)); _Pragma("unroll") for (int _i = 0; _i < 2; ++_i) { unsigned vo_ = (voff)[_i]; asm volatile("" : "+v"(vo_));        \
;         __builtin_amdgcn_global_load_lds((const unsigned*)(gb_ + vo_), (PG8_LAS unsigned*)(lds + (bufoff) + ldsw + _i * 8192), 16, 0, 0); } } while (0)
; #define PG8_LDA(dst, b, h) do { _Pragma("unroll") for (int m = 0; m < 4; ++m) _Pragma("unroll") for (int k = 0; k < 2; ++k) dst[m][k] = *(const PG8_LAS bf16x8*)(lds + PG8_SA(b, h) + aoff + m * 2048 + k * 1024); } while (0)
; #define PG8_LDB(dst, b, h) do { _Pragma("unroll") for (int n = 0; n < 2; ++n) _Pragma("unroll") for (int k = 0; k < 2; ++k) dst[n][k] = *(const PG8_LAS bf16x8*)(lds + PG8_SB(b, h) + boff + n * 2048 + k * 1024); } while (0)
; #define PG8_MMA(ai, bj, At, Bt) do { __builtin_amdgcn_s_setprio(1); _Pragma("unroll") for (int m = 0; m < 4; ++m) _Pragma("unroll") for (int n = 0; n < 2; ++n) _Pragma("unroll") for (int k = 0; k < 2; ++k) \
;         acc[ai][bj][m][n] = __builtin_amdgcn_mfma_f32_16x16x32_bf16(Bt[n][k], At[m][k], acc[ai][bj][m][n], 0, 0, 0); __builtin_amdgcn_s_setprio(0); } while (0)
; template <class Epi, class Sched, bool ALIGN_EPI = false, bool SP2 = false>
; __device__ __forceinline__ void gemm_phase(PG8_LAS unsigned char* lds, const Gemm g, const Sched& S, const Epi& E) {
;     ...
;         for (int t = 0; t < nt; t += 2) {
;             const bool last = (t == nt - 2);
;             const char* a1 = cA + (size_t)(t + 1) * kstep;
;             const char* a2 = last ? nA : cA + (size_t)(t + 2) * kstep; const char* b2 = last ? nB : cB + (size_t)(t + 2) * kstep;
;             const char* a3 = a2 + kstep; const char* b3 = b2 + kstep;
;             if (last && has_next) S.a_ready(nxt);
;             if constexpr (SP2) {
;             PG8_LDB(B0, 0, 0); PG8_LDB(B1, 0, 1); PG8_SCHED; PG8_LDA(At, 0, 0); PG8_STAGE(PG8_SA(1, 1), a1 + hstep, voffA);
;             PG8_WAIT_V(8); PG8_WAIT_L(0); PG8_BAR; PG8_MMA(0, 0, At, B0); PG8_MMA(0, 1, At, B1); PG8_BAR; PG8_SCHED;
;             PG8_LDA(At, 0, 1); PG8_STAGE(PG8_SB(0, 0), b2, voffB); PG8_STAGE(PG8_SB(0, 1), b2 + hstep, voffB); PG8_STAGE(PG8_SA(0, 0), a2, voffA);
;             PG8_WAIT_V(8); PG8_WAIT_L(0); PG8_BAR; PG8_MMA(1, 0, At, B0); PG8_MMA(1, 1, At, B1); PG8_BAR; PG8_SCHED;
.LBB0_232:
	s_add_u32 s2, s0, 0x100
	s_addc_u32 s3, s1, 0
	s_cmp_eq_u32 s30, 28
	s_cselect_b32 s10, s25, s2
	s_cselect_b32 s11, s24, s3
	s_cselect_b32 s8, s27, s28
	s_cselect_b32 s9, s26, s29
	s_add_u32 s6, s10, 0x80
	s_addc_u32 s7, s11, 0
	s_add_i32 s31, 0, 0x10000
	s_add_i32 s33, 0, 0x14000
	v_add_u32_e32 v78, s31, v221
	v_add_u32_e32 v158, s33, v221
	ds_read_b128 v[66:69], v78
	ds_read_b128 v[70:73], v78 offset:1024
	ds_read_b128 v[74:77], v78 offset:2048
	ds_read_b128 v[78:81], v78 offset:3072
	ds_read_b128 v[146:149], v158
	ds_read_b128 v[150:153], v158 offset:1024
	ds_read_b128 v[154:157], v158 offset:2048
	ds_read_b128 v[158:161], v158 offset:3072
	s_add_u32 s0, s0, 0x80080
	s_addc_u32 s1, s1, 0
	v_mov_b32_e32 v162, v1
	ds_read_b128 v[178:181], v223
	ds_read_b128 v[182:185], v223 offset:1024
	ds_read_b128 v[192:195], v223 offset:2048
	ds_read_b128 v[196:199], v223 offset:3072
	ds_read_b128 v[200:203], v223 offset:4096
	ds_read_b128 v[204:207], v223 offset:5120
	ds_read_b128 v[208:211], v223 offset:6144
	ds_read_b128 v[212:215], v223 offset:7168
	s_add_i32 m0, s13, 0xc000
	s_nop 0
	global_load_lds_dwordx4 v162, s[0:1]
	v_mov_b32_e32 v162, v191
	s_add_i32 m0, s13, 0xe000
	s_nop 0
	global_load_lds_dwordx4 v162, s[0:1]
	s_waitcnt vmcnt(8)
	s_waitcnt lgkmcnt(0)
	s_barrier
	s_setprio 1
	s_waitcnt lgkmcnt(0)
	v_mfma_f32_16x16x32_bf16 v[142:145], v[66:69], v[178:181], v[142:145]
	v_mfma_f32_16x16x32_bf16 v[142:145], v[70:73], v[182:185], v[142:145]
	v_mfma_f32_16x16x32_bf16 v[134:137], v[66:69], v[192:195], v[134:137]
	v_mfma_f32_16x16x32_bf16 v[134:137], v[70:73], v[196:199], v[134:137]
	v_mfma_f32_16x16x32_bf16 v[126:129], v[66:69], v[200:203], v[126:129]
	v_mfma_f32_16x16x32_bf16 v[126:129], v[70:73], v[204:207], v[126:129]
	v_mfma_f32_16x16x32_bf16 v[118:121], v[66:69], v[208:211], v[118:121]
	v_mfma_f32_16x16x32_bf16 v[118:121], v[70:73], v[212:215], v[118:121]
	v_mfma_f32_16x16x32_bf16 v[138:141], v[74:77], v[178:181], v[138:141]
	v_mfma_f32_16x16x32_bf16 v[138:141], v[78:81], v[182:185], v[138:141]
	v_mfma_f32_16x16x32_bf16 v[130:133], v[74:77], v[192:195], v[130:133]
	v_mfma_f32_16x16x32_bf16 v[130:133], v[78:81], v[196:199], v[130:133]
	v_mfma_f32_16x16x32_bf16 v[122:125], v[74:77], v[200:203], v[122:125]
	v_mfma_f32_16x16x32_bf16 v[122:125], v[78:81], v[204:207], v[122:125]
	v_mfma_f32_16x16x32_bf16 v[114:117], v[74:77], v[208:211], v[114:117]
	v_mfma_f32_16x16x32_bf16 v[114:117], v[78:81], v[212:215], v[114:117]
	s_setprio 0
	s_setprio 1
	v_mfma_f32_16x16x32_bf16 v[62:65], v[146:149], v[178:181], v[62:65]
	v_mfma_f32_16x16x32_bf16 v[62:65], v[150:153], v[182:185], v[62:65]
	v_mfma_f32_16x16x32_bf16 v[54:57], v[146:149], v[192:195], v[54:57]
	v_mfma_f32_16x16x32_bf16 v[54:57], v[150:153], v[196:199], v[54:57]
	v_mfma_f32_16x16x32_bf16 v[46:49], v[146:149], v[200:203], v[46:49]
	v_mfma_f32_16x16x32_bf16 v[46:49], v[150:153], v[204:207], v[46:49]
	v_mfma_f32_16x16x32_bf16 v[38:41], v[146:149], v[208:211], v[38:41]
	v_mfma_f32_16x16x32_bf16 v[38:41], v[150:153], v[212:215], v[38:41]
	v_mfma_f32_16x16x32_bf16 v[58:61], v[154:157], v[178:181], v[58:61]
	v_mfma_f32_16x16x32_bf16 v[58:61], v[158:161], v[182:185], v[58:61]
	v_mfma_f32_16x16x32_bf16 v[50:53], v[154:157], v[192:195], v[50:53]
	v_mfma_f32_16x16x32_bf16 v[50:53], v[158:161], v[196:199], v[50:53]
	v_mfma_f32_16x16x32_bf16 v[42:45], v[154:157], v[200:203], v[42:45]
	v_mfma_f32_16x16x32_bf16 v[42:45], v[158:161], v[204:207], v[42:45]
	v_mfma_f32_16x16x32_bf16 v[34:37], v[154:157], v[208:211], v[34:37]
	v_mfma_f32_16x16x32_bf16 v[34:37], v[158:161], v[212:215], v[34:37]
	s_setprio 0
	s_barrier
	s_mov_b64 s[0:1], s[8:9]
	v_mov_b32_e32 v162, v189
	s_add_i32 s31, s31, s12
	ds_read_b128 v[178:181], v223 offset:16384
	ds_read_b128 v[182:185], v223 offset:17408
	ds_read_b128 v[192:195], v223 offset:18432
	ds_read_b128 v[196:199], v223 offset:19456
	ds_read_b128 v[200:203], v223 offset:20480
	ds_read_b128 v[204:207], v223 offset:21504
	ds_read_b128 v[208:211], v223 offset:22528
	ds_read_b128 v[212:215], v223 offset:23552
	s_mov_b32 m0, s31
	s_nop 0
	global_load_lds_dwordx4 v162, s[0:1]
	v_mov_b32_e32 v162, v219
	s_add_i32 m0, s31, 0x2000
	s_nop 0
	global_load_lds_dwordx4 v162, s[0:1]
	s_add_u32 s0, s8, 0x80000
	s_addc_u32 s1, s9, 0
	v_mov_b32_e32 v162, v189
	s_add_i32 s31, s33, s12
	s_mov_b32 m0, s31
	s_nop 0
	global_load_lds_dwordx4 v162, s[0:1]
	v_mov_b32_e32 v162, v219
	s_add_i32 m0, s31, 0x2000
	s_nop 0
	global_load_lds_dwordx4 v162, s[0:1]
	s_mov_b64 s[0:1], s[10:11]
	v_mov_b32_e32 v162, v1
	s_mov_b32 m0, s13
	s_nop 0
	global_load_lds_dwordx4 v162, s[0:1]
	v_mov_b32_e32 v162, v191
	s_mov_b32 m0, s14
	s_nop 0
	global_load_lds_dwordx4 v162, s[0:1]
	s_waitcnt vmcnt(8)
	s_waitcnt lgkmcnt(0)
	s_barrier
; #define PG8_STAGE(bufoff, gbase, voff) do { const char* gb_ = (const char*)(gbase); asm volatile("" : "+s"(gb_)); _Pragma("unroll") for (int _i = 0; _i < 2; ++_i) { unsigned vo_ = (voff)[_i]; asm volatile("" : "+v"(vo_));        \
;         __builtin_amdgcn_global_load_lds((const unsigned*)(gb_ + vo_), (PG8_LAS unsigned*)(lds + (bufoff) + ldsw + _i * 8192), 16, 0, 0); } } while (0)
; #define PG8_LDA(dst, b, h) do { _Pragma("unroll") for (int m = 0; m < 4; ++m) _Pragma("unroll") for (int k = 0; k < 2; ++k) dst[m][k] = *(const PG8_LAS bf16x8*)(lds + PG8_SA(b, h) + aoff + m * 2048 + k * 1024); } while (0)
; #define PG8_LDB(dst, b, h) do { _Pragma("unroll") for (int n = 0; n < 2; ++n) _Pragma("unroll") for (int k = 0; k < 2; ++k) dst[n][k] = *(const PG8_LAS bf16x8*)(lds + PG8_SB(b, h) + boff + n * 2048 + k * 1024); } while (0)
; #define PG8_MMA(ai, bj, At, Bt) do { __builtin_amdgcn_s_setprio(1); _Pragma("unroll") for (int m = 0; m < 4; ++m) _Pragma("unroll") for (int n = 0; n < 2; ++n) _Pragma("unroll") for (int k = 0; k < 2; ++k) \
;         acc[ai][bj][m][n] = __builtin_amdgcn_mfma_f32_16x16x32_bf16(Bt[n][k], At[m][k], acc[ai][bj][m][n], 0, 0, 0); __builtin_amdgcn_s_setprio(0); } while (0)
; #define PG8_WAIT_V(n) asm volatile("s_waitcnt vmcnt(" #n ")" ::: "memory")
; #define PG8_WAIT_L(n) asm volatile("s_waitcnt lgkmcnt(" #n ")" ::: "memory")
; #define PG8_BAR __builtin_amdgcn_s_barrier()
; #define PG8_SCHED __builtin_amdgcn_sched_barrier(0)
; template <class Epi, class Sched, bool ALIGN_EPI = false, bool SP2 = false>
; __device__ __forceinline__ void gemm_phase(PG8_LAS unsigned char* lds, const Gemm g, const Sched& S, const Epi& E) {
;     ...
;             PG8_WAIT_V(8); PG8_WAIT_L(0); PG8_BAR; PG8_MMA(0, 0, At, B0); PG8_MMA(0, 1, At, B1); PG8_BAR; PG8_SCHED;
;             PG8_LDA(At, 0, 1); PG8_STAGE(PG8_SB(0, 0), b2, voffB); PG8_STAGE(PG8_SB(0, 1), b2 + hstep, voffB); PG8_STAGE(PG8_SA(0, 0), a2, voffA);
;             PG8_WAIT_V(8); PG8_WAIT_L(0); PG8_BAR; PG8_MMA(1, 0, At, B0); PG8_MMA(1, 1, At, B1); PG8_BAR; PG8_SCHED;
;             PG8_LDB(B0, 1, 0); PG8_LDB(B1, 1, 1); PG8_SCHED; PG8_LDA(At, 1, 0); PG8_STAGE(PG8_SA(0, 1), a2 + hstep, voffA);
;             PG8_WAIT_V(8); PG8_WAIT_L(0); PG8_BAR; PG8_MMA(0, 0, At, B0); PG8_MMA(0, 1, At, B1); PG8_BAR; PG8_SCHED;
	s_setprio 1
	s_waitcnt lgkmcnt(0)
	v_mfma_f32_16x16x32_bf16 v[110:113], v[66:69], v[178:181], v[110:113]
	v_mfma_f32_16x16x32_bf16 v[106:109], v[74:77], v[178:181], v[106:109]
	v_mfma_f32_16x16x32_bf16 v[102:105], v[66:69], v[192:195], v[102:105]
	v_mfma_f32_16x16x32_bf16 v[98:101], v[74:77], v[192:195], v[98:101]
	v_mfma_f32_16x16x32_bf16 v[94:97], v[66:69], v[200:203], v[94:97]
	v_mfma_f32_16x16x32_bf16 v[90:93], v[74:77], v[200:203], v[90:93]
	v_mfma_f32_16x16x32_bf16 v[66:69], v[66:69], v[208:211], v[86:89]
	v_mfma_f32_16x16x32_bf16 v[110:113], v[70:73], v[182:185], v[110:113]
	v_mfma_f32_16x16x32_bf16 v[106:109], v[78:81], v[182:185], v[106:109]
	v_mfma_f32_16x16x32_bf16 v[102:105], v[70:73], v[196:199], v[102:105]
	v_mfma_f32_16x16x32_bf16 v[98:101], v[78:81], v[196:199], v[98:101]
	v_mfma_f32_16x16x32_bf16 v[94:97], v[70:73], v[204:207], v[94:97]
	v_mfma_f32_16x16x32_bf16 v[90:93], v[78:81], v[204:207], v[90:93]
	v_mfma_f32_16x16x32_bf16 v[66:69], v[70:73], v[212:215], v[66:69]
	v_mfma_f32_16x16x32_bf16 v[70:73], v[74:77], v[208:211], v[82:85]
	v_mfma_f32_16x16x32_bf16 v[70:73], v[78:81], v[212:215], v[70:73]
	s_setprio 0
	s_setprio 1
	v_mfma_f32_16x16x32_bf16 v[30:33], v[146:149], v[178:181], v[30:33]
	v_mfma_f32_16x16x32_bf16 v[30:33], v[150:153], v[182:185], v[30:33]
	v_mfma_f32_16x16x32_bf16 v[22:25], v[146:149], v[192:195], v[22:25]
	v_mfma_f32_16x16x32_bf16 v[22:25], v[150:153], v[196:199], v[22:25]
	v_mfma_f32_16x16x32_bf16 v[14:17], v[146:149], v[200:203], v[14:17]
	v_mfma_f32_16x16x32_bf16 v[14:17], v[150:153], v[204:207], v[14:17]
	v_mfma_f32_16x16x32_bf16 v[6:9], v[146:149], v[208:211], v[6:9]
	v_mfma_f32_16x16x32_bf16 v[6:9], v[150:153], v[212:215], v[6:9]
	v_mfma_f32_16x16x32_bf16 v[26:29], v[154:157], v[178:181], v[26:29]
	v_mfma_f32_16x16x32_bf16 v[26:29], v[158:161], v[182:185], v[26:29]
	v_mfma_f32_16x16x32_bf16 v[18:21], v[154:157], v[192:195], v[18:21]
	v_mfma_f32_16x16x32_bf16 v[18:21], v[158:161], v[196:199], v[18:21]
	v_mfma_f32_16x16x32_bf16 v[10:13], v[154:157], v[200:203], v[10:13]
	v_mfma_f32_16x16x32_bf16 v[10:13], v[158:161], v[204:207], v[10:13]
	v_mfma_f32_16x16x32_bf16 v[2:5], v[154:157], v[208:211], v[2:5]
	v_mfma_f32_16x16x32_bf16 v[2:5], v[158:161], v[212:215], v[2:5]
	s_setprio 0
	s_barrier
	s_add_i32 s31, 0, 0x18000
	v_add_u32_e32 v86, s31, v221
	s_add_i32 s33, 0, 0x1c000
	ds_read_b128 v[74:77], v86
	ds_read_b128 v[78:81], v86 offset:1024
	ds_read_b128 v[82:85], v86 offset:2048
	ds_read_b128 v[146:149], v86 offset:3072
	v_add_u32_e32 v86, s33, v221
	ds_read_b128 v[150:153], v86
	ds_read_b128 v[154:157], v86 offset:1024
	ds_read_b128 v[158:161], v86 offset:2048
	ds_read_b128 v[178:181], v86 offset:3072
	s_add_u32 s0, s10, 0x80000
	s_addc_u32 s1, s11, 0
	v_mov_b32_e32 v162, v1
	s_mov_b32 m0, s15
	ds_read_b128 v[86:89], v223 offset:32768
	ds_read_b128 v[182:185], v223 offset:33792
	ds_read_b128 v[192:195], v223 offset:34816
	ds_read_b128 v[196:199], v223 offset:35840
	ds_read_b128 v[200:203], v223 offset:36864
	ds_read_b128 v[204:207], v223 offset:37888
	ds_read_b128 v[208:211], v223 offset:38912
	ds_read_b128 v[212:215], v223 offset:39936
	s_nop 0
	global_load_lds_dwordx4 v162, s[0:1]
	v_mov_b32_e32 v162, v191
	s_mov_b32 m0, s16
	s_nop 0
	global_load_lds_dwordx4 v162, s[0:1]
	s_waitcnt vmcnt(8)
	s_waitcnt lgkmcnt(0)
	s_barrier
	s_setprio 1
	s_waitcnt lgkmcnt(0)
	v_mfma_f32_16x16x32_bf16 v[142:145], v[74:77], v[86:89], v[142:145]
	v_mfma_f32_16x16x32_bf16 v[142:145], v[78:81], v[182:185], v[142:145]
	v_mfma_f32_16x16x32_bf16 v[134:137], v[74:77], v[192:195], v[134:137]
	v_mfma_f32_16x16x32_bf16 v[134:137], v[78:81], v[196:199], v[134:137]
	v_mfma_f32_16x16x32_bf16 v[126:129], v[74:77], v[200:203], v[126:129]
	v_mfma_f32_16x16x32_bf16 v[126:129], v[78:81], v[204:207], v[126:129]
	v_mfma_f32_16x16x32_bf16 v[118:121], v[74:77], v[208:211], v[118:121]
	v_mfma_f32_16x16x32_bf16 v[118:121], v[78:81], v[212:215], v[118:121]
	v_mfma_f32_16x16x32_bf16 v[138:141], v[82:85], v[86:89], v[138:141]
	v_mfma_f32_16x16x32_bf16 v[138:141], v[146:149], v[182:185], v[138:141]
	v_mfma_f32_16x16x32_bf16 v[130:133], v[82:85], v[192:195], v[130:133]
	v_mfma_f32_16x16x32_bf16 v[130:133], v[146:149], v[196:199], v[130:133]
	v_mfma_f32_16x16x32_bf16 v[122:125], v[82:85], v[200:203], v[122:125]
	v_mfma_f32_16x16x32_bf16 v[122:125], v[146:149], v[204:207], v[122:125]
	v_mfma_f32_16x16x32_bf16 v[114:117], v[82:85], v[208:211], v[114:117]
	v_mfma_f32_16x16x32_bf16 v[114:117], v[146:149], v[212:215], v[114:117]
	s_setprio 0
	s_setprio 1
	v_mfma_f32_16x16x32_bf16 v[62:65], v[150:153], v[86:89], v[62:65]
	v_mfma_f32_16x16x32_bf16 v[62:65], v[154:157], v[182:185], v[62:65]
	v_mfma_f32_16x16x32_bf16 v[54:57], v[150:153], v[192:195], v[54:57]
	v_mfma_f32_16x16x32_bf16 v[54:57], v[154:157], v[196:199], v[54:57]
	v_mfma_f32_16x16x32_bf16 v[46:49], v[150:153], v[200:203], v[46:49]
	v_mfma_f32_16x16x32_bf16 v[46:49], v[154:157], v[204:207], v[46:49]
	v_mfma_f32_16x16x32_bf16 v[38:41], v[150:153], v[208:211], v[38:41]
	v_mfma_f32_16x16x32_bf16 v[38:41], v[154:157], v[212:215], v[38:41]
	v_mfma_f32_16x16x32_bf16 v[58:61], v[158:161], v[86:89], v[58:61]
	v_mfma_f32_16x16x32_bf16 v[58:61], v[178:181], v[182:185], v[58:61]
	v_mfma_f32_16x16x32_bf16 v[50:53], v[158:161], v[192:195], v[50:53]
	v_mfma_f32_16x16x32_bf16 v[50:53], v[178:181], v[196:199], v[50:53]
	v_mfma_f32_16x16x32_bf16 v[42:45], v[158:161], v[200:203], v[42:45]
	v_mfma_f32_16x16x32_bf16 v[42:45], v[178:181], v[204:207], v[42:45]
	v_mfma_f32_16x16x32_bf16 v[34:37], v[158:161], v[208:211], v[34:37]
	v_mfma_f32_16x16x32_bf16 v[34:37], v[178:181], v[212:215], v[34:37]
	s_setprio 0
	s_barrier
; #define PG8_STAGE(bufoff, gbase, voff) do { const char* gb_ = (const char*)(gbase); asm volatile("" : "+s"(gb_)); _Pragma("unroll") for (int _i = 0; _i < 2; ++_i) { unsigned vo_ = (voff)[_i]; asm volatile("" : "+v"(vo_));        \
;         __builtin_amdgcn_global_load_lds((const unsigned*)(gb_ + vo_), (PG8_LAS unsigned*)(lds + (bufoff) + ldsw + _i * 8192), 16, 0, 0); } } while (0)
; #define PG8_LDA(dst, b, h) do { _Pragma("unroll") for (int m = 0; m < 4; ++m) _Pragma("unroll") for (int k = 0; k < 2; ++k) dst[m][k] = *(const PG8_LAS bf16x8*)(lds + PG8_SA(b, h) + aoff + m * 2048 + k * 1024); } while (0)
; #define PG8_MMA(ai, bj, At, Bt) do { __builtin_amdgcn_s_setprio(1); _Pragma("unroll") for (int m = 0; m < 4; ++m) _Pragma("unroll") for (int n = 0; n < 2; ++n) _Pragma("unroll") for (int k = 0; k < 2; ++k) \
;         acc[ai][bj][m][n] = __builtin_amdgcn_mfma_f32_16x16x32_bf16(Bt[n][k], At[m][k], acc[ai][bj][m][n], 0, 0, 0); __builtin_amdgcn_s_setprio(0); } while (0)
; #define PG8_WAIT_V(n) asm volatile("s_waitcnt vmcnt(" #n ")" ::: "memory")
; #define PG8_WAIT_L(n) asm volatile("s_waitcnt lgkmcnt(" #n ")" ::: "memory")
; #define PG8_BAR __builtin_amdgcn_s_barrier()
; #define PG8_SCHED __builtin_amdgcn_sched_barrier(0)
; template <class Epi, class Sched, bool ALIGN_EPI = false, bool SP2 = false>
; __device__ __forceinline__ void gemm_phase(PG8_LAS unsigned char* lds, const Gemm g, const Sched& S, const Epi& E) {
;     ...
;             PG8_LDA(At, 1, 1); PG8_STAGE(PG8_SB(1, 0), b3, voffB); PG8_STAGE(PG8_SB(1, 1), b3 + hstep, voffB); PG8_STAGE(PG8_SA(1, 0), a3, voffA);
;             PG8_WAIT_V(8); PG8_WAIT_L(0); PG8_BAR; PG8_MMA(1, 0, At, B0); PG8_MMA(1, 1, At, B1); PG8_BAR; PG8_SCHED;
;     ...
;         if constexpr (ALIGN_EPI) { if (wr == 0) PG8_BAR; }
	s_add_u32 s0, s8, 0x80
	s_addc_u32 s1, s9, 0
	v_mov_b32_e32 v86, v189
	s_add_i32 s10, s31, s12
	ds_read_b128 v[182:185], v223 offset:49152
	ds_read_b128 v[192:195], v223 offset:50176
	ds_read_b128 v[196:199], v223 offset:51200
	ds_read_b128 v[200:203], v223 offset:52224
	ds_read_b128 v[204:207], v223 offset:53248
	ds_read_b128 v[208:211], v223 offset:54272
	ds_read_b128 v[212:215], v223 offset:55296
	ds_read_b128 v[224:227], v223 offset:56320
	s_mov_b32 m0, s10
	s_nop 0
	global_load_lds_dwordx4 v86, s[0:1]
	v_mov_b32_e32 v86, v219
	s_add_i32 m0, s10, 0x2000
	s_nop 0
	global_load_lds_dwordx4 v86, s[0:1]
	s_add_u32 s0, s8, 0x80080
	s_addc_u32 s1, s9, 0
	v_mov_b32_e32 v86, v189
	s_add_i32 s8, s33, s12
	s_mov_b32 m0, s8
	s_nop 0
	global_load_lds_dwordx4 v86, s[0:1]
	v_mov_b32_e32 v86, v219
	s_add_i32 m0, s8, 0x2000
	s_nop 0
	global_load_lds_dwordx4 v86, s[0:1]
	v_mov_b32_e32 v86, v1
	s_mov_b32 m0, s19
	s_nop 0
	global_load_lds_dwordx4 v86, s[6:7]
	v_mov_b32_e32 v86, v191
	s_mov_b32 m0, s20
	s_nop 0
	global_load_lds_dwordx4 v86, s[6:7]
	s_waitcnt vmcnt(8)
	s_waitcnt lgkmcnt(0)
	s_barrier
	s_setprio 1
	s_waitcnt lgkmcnt(0)
	v_mfma_f32_16x16x32_bf16 v[86:89], v[74:77], v[182:185], v[110:113]
	v_mfma_f32_16x16x32_bf16 v[110:113], v[78:81], v[192:195], v[86:89]
	v_mfma_f32_16x16x32_bf16 v[86:89], v[82:85], v[182:185], v[106:109]
	v_mfma_f32_16x16x32_bf16 v[106:109], v[146:149], v[192:195], v[86:89]
	v_mfma_f32_16x16x32_bf16 v[86:89], v[74:77], v[196:199], v[102:105]
	v_mfma_f32_16x16x32_bf16 v[102:105], v[78:81], v[200:203], v[86:89]
	v_mfma_f32_16x16x32_bf16 v[86:89], v[82:85], v[196:199], v[98:101]
	v_mfma_f32_16x16x32_bf16 v[98:101], v[146:149], v[200:203], v[86:89]
	v_mfma_f32_16x16x32_bf16 v[86:89], v[74:77], v[204:207], v[94:97]
	v_mfma_f32_16x16x32_bf16 v[94:97], v[78:81], v[208:211], v[86:89]
	v_mfma_f32_16x16x32_bf16 v[86:89], v[82:85], v[204:207], v[90:93]
	v_mfma_f32_16x16x32_bf16 v[66:69], v[74:77], v[212:215], v[66:69]
	v_mfma_f32_16x16x32_bf16 v[90:93], v[146:149], v[208:211], v[86:89]
	v_mfma_f32_16x16x32_bf16 v[86:89], v[78:81], v[224:227], v[66:69]
	v_mfma_f32_16x16x32_bf16 v[66:69], v[82:85], v[212:215], v[70:73]
	v_mfma_f32_16x16x32_bf16 v[82:85], v[146:149], v[224:227], v[66:69]
	s_setprio 0
	s_setprio 1
	v_mfma_f32_16x16x32_bf16 v[30:33], v[150:153], v[182:185], v[30:33]
	v_mfma_f32_16x16x32_bf16 v[30:33], v[154:157], v[192:195], v[30:33]
	v_mfma_f32_16x16x32_bf16 v[22:25], v[150:153], v[196:199], v[22:25]
	v_mfma_f32_16x16x32_bf16 v[22:25], v[154:157], v[200:203], v[22:25]
	v_mfma_f32_16x16x32_bf16 v[14:17], v[150:153], v[204:207], v[14:17]
	v_mfma_f32_16x16x32_bf16 v[14:17], v[154:157], v[208:211], v[14:17]
	v_mfma_f32_16x16x32_bf16 v[6:9], v[150:153], v[212:215], v[6:9]
	v_mfma_f32_16x16x32_bf16 v[6:9], v[154:157], v[224:227], v[6:9]
	v_mfma_f32_16x16x32_bf16 v[26:29], v[158:161], v[182:185], v[26:29]
	v_mfma_f32_16x16x32_bf16 v[26:29], v[178:181], v[192:195], v[26:29]
	v_mfma_f32_16x16x32_bf16 v[18:21], v[158:161], v[196:199], v[18:21]
	v_mfma_f32_16x16x32_bf16 v[18:21], v[178:181], v[200:203], v[18:21]
	v_mfma_f32_16x16x32_bf16 v[10:13], v[158:161], v[204:207], v[10:13]
	v_mfma_f32_16x16x32_bf16 v[10:13], v[178:181], v[208:211], v[10:13]
	v_mfma_f32_16x16x32_bf16 v[2:5], v[158:161], v[212:215], v[2:5]
	v_mfma_f32_16x16x32_bf16 v[2:5], v[178:181], v[224:227], v[2:5]
	s_setprio 0
	s_barrier
	s_add_i32 s30, s30, 2
	s_add_u32 s28, s28, 0x100
	s_addc_u32 s29, s29, 0
	s_cmp_gt_u32 s30, 29
	s_mov_b64 s[0:1], s[2:3]
	s_cbranch_scc0 .LBB0_232
	s_and_b64 vcc, exec, s[44:45]
	s_cbranch_vccz .LBB0_235
	s_barrier

; #define PG8_STAGE(bufoff, gbase, voff) do { const char* gb_ = (const char*)(gbase); asm volatile("" : "+s"(gb_)); _Pragma("unroll") for (int _i = 0; _i < 2; ++_i) { unsigned vo_ = (voff)[_i]; asm volatile("" : "+v"(vo_));        \
;         __builtin_amdgcn_global_load_lds((const unsigned*)(gb_ + vo_), (PG8_LAS unsigned*)(lds + (bufoff) + ldsw + _i * 8192), 16, 0, 0); } } while (0)
; #define PG8_LDA(dst, b, h) do { _Pragma("unroll") for (int m = 0; m < 4; ++m) _Pragma("unroll") for (int k = 0; k < 2; ++k) dst[m][k] = *(const PG8_LAS bf16x8*)(lds + PG8_SA(b, h) + aoff + m * 2048 + k * 1024); } while (0)
; #define PG8_LDB(dst, b, h) do { _Pragma("unroll") for (int n = 0; n < 2; ++n) _Pragma("unroll") for (int k = 0; k < 2; ++k) dst[n][k] = *(const PG8_LAS bf16x8*)(lds + PG8_SB(b, h) + boff + n * 2048 + k * 1024); } while (0)
; #define PG8_MMA(ai, bj, At, Bt) do { __builtin_amdgcn_s_setprio(1); _Pragma("unroll") for (int m = 0; m < 4; ++m) _Pragma("unroll") for (int n = 0; n < 2; ++n) _Pragma("unroll") for (int k = 0; k < 2; ++k) \
;         acc[ai][bj][m][n] = __builtin_amdgcn_mfma_f32_16x16x32_bf16(Bt[n][k], At[m][k], acc[ai][bj][m][n], 0, 0, 0); __builtin_amdgcn_s_setprio(0); } while (0)
; #define PG8_WAIT_V(n) asm volatile("s_waitcnt vmcnt(" #n ")" ::: "memory")
; template <class Epi, class Sched, bool ALIGN_EPI = false, bool SP2 = false>
; __device__ __forceinline__ void gemm_phase(PG8_LAS unsigned char* lds, const Gemm g, const Sched& S, const Epi& E) {
;     ...
;             const bool last = (t == nt - 2);
;             const char* a1 = cA + (size_t)(t + 1) * kstep;
;             const char* a2 = last ? nA : cA + (size_t)(t + 2) * kstep; const char* b2 = last ? nB : cB + (size_t)(t + 2) * kstep;
;             const char* a3 = a2 + kstep; const char* b3 = b2 + kstep;
;             if (last && has_next) S.a_ready(nxt);
;             if constexpr (SP2) {
;             PG8_LDB(B0, 0, 0); PG8_LDB(B1, 0, 1); PG8_SCHED; PG8_LDA(At, 0, 0); PG8_STAGE(PG8_SA(1, 1), a1 + hstep, voffA);
;             PG8_WAIT_V(8); PG8_WAIT_L(0); PG8_BAR; PG8_MMA(0, 0, At, B0); PG8_MMA(0, 1, At, B1); PG8_BAR; PG8_SCHED;
;             PG8_LDA(At, 0, 1); PG8_STAGE(PG8_SB(0, 0), b2, voffB); PG8_STAGE(PG8_SB(0, 1), b2 + hstep, voffB); PG8_STAGE(PG8_SA(0, 0), a2, voffA);
;             PG8_WAIT_V(8); PG8_WAIT_L(0); PG8_BAR; PG8_MMA(1, 0, At, B0); PG8_MMA(1, 1, At, B1); PG8_BAR; PG8_SCHED;
.LBB0_555:
	s_add_u32 s6, s4, 0x100
	s_addc_u32 s7, s5, 0
	s_cmp_eq_u32 s51, 28
	s_cselect_b32 s12, s35, s6
	s_cselect_b32 s13, s34, s7
	s_cselect_b32 s10, s39, s40
	s_cselect_b32 s11, s38, s49
	s_add_u32 s8, s12, 0x80
	s_addc_u32 s9, s13, 0
	s_add_i32 s56, 0, 0x10000
	s_add_i32 s57, 0, 0x14000
	v_add_u32_e32 v102, s56, v208
	v_add_u32_e32 v158, s57, v208
	ds_read_b128 v[26:29], v102
	ds_read_b128 v[30:33], v102 offset:1024
	ds_read_b128 v[98:101], v102 offset:2048
	ds_read_b128 v[102:105], v102 offset:3072
	ds_read_b128 v[146:149], v158
	ds_read_b128 v[150:153], v158 offset:1024
	ds_read_b128 v[154:157], v158 offset:2048
	ds_read_b128 v[158:161], v158 offset:3072
	s_add_u32 s4, s4, 0x80080
	s_addc_u32 s5, s5, 0
	v_mov_b32_e32 v211, v1
	ds_read_b128 v[178:181], v210
	ds_read_b128 v[182:185], v210 offset:1024
	ds_read_b128 v[186:189], v210 offset:2048
	ds_read_b128 v[190:193], v210 offset:3072
	ds_read_b128 v[194:197], v210 offset:4096
	ds_read_b128 v[198:201], v210 offset:5120
	ds_read_b128 v[202:205], v210 offset:6144
	ds_read_b128 v[212:215], v210 offset:7168
	s_add_i32 m0, s18, 0xc000
	s_nop 0
	global_load_lds_dwordx4 v211, s[4:5]
	v_mov_b32_e32 v211, v164
	s_add_i32 m0, s18, 0xe000
	s_nop 0
	global_load_lds_dwordx4 v211, s[4:5]
	s_waitcnt vmcnt(8)
	s_waitcnt lgkmcnt(0)
	s_barrier
	s_setprio 1
	s_waitcnt lgkmcnt(0)
	v_mfma_f32_16x16x32_bf16 v[142:145], v[26:29], v[178:181], v[142:145]
	v_mfma_f32_16x16x32_bf16 v[142:145], v[30:33], v[182:185], v[142:145]
	v_mfma_f32_16x16x32_bf16 v[134:137], v[26:29], v[186:189], v[134:137]
	v_mfma_f32_16x16x32_bf16 v[134:137], v[30:33], v[190:193], v[134:137]
	v_mfma_f32_16x16x32_bf16 v[126:129], v[26:29], v[194:197], v[126:129]
	v_mfma_f32_16x16x32_bf16 v[126:129], v[30:33], v[198:201], v[126:129]
	v_mfma_f32_16x16x32_bf16 v[118:121], v[26:29], v[202:205], v[118:121]
	v_mfma_f32_16x16x32_bf16 v[118:121], v[30:33], v[212:215], v[118:121]
	v_mfma_f32_16x16x32_bf16 v[138:141], v[98:101], v[178:181], v[138:141]
	v_mfma_f32_16x16x32_bf16 v[138:141], v[102:105], v[182:185], v[138:141]
	v_mfma_f32_16x16x32_bf16 v[130:133], v[98:101], v[186:189], v[130:133]
	v_mfma_f32_16x16x32_bf16 v[130:133], v[102:105], v[190:193], v[130:133]
	v_mfma_f32_16x16x32_bf16 v[122:125], v[98:101], v[194:197], v[122:125]
	v_mfma_f32_16x16x32_bf16 v[122:125], v[102:105], v[198:201], v[122:125]
	v_mfma_f32_16x16x32_bf16 v[114:117], v[98:101], v[202:205], v[114:117]
	v_mfma_f32_16x16x32_bf16 v[114:117], v[102:105], v[212:215], v[114:117]
	s_setprio 0
	s_setprio 1
	v_mfma_f32_16x16x32_bf16 v[70:73], v[146:149], v[178:181], v[70:73]
	v_mfma_f32_16x16x32_bf16 v[70:73], v[150:153], v[182:185], v[70:73]
	v_mfma_f32_16x16x32_bf16 v[62:65], v[146:149], v[186:189], v[62:65]
	v_mfma_f32_16x16x32_bf16 v[62:65], v[150:153], v[190:193], v[62:65]
	v_mfma_f32_16x16x32_bf16 v[54:57], v[146:149], v[194:197], v[54:57]
	v_mfma_f32_16x16x32_bf16 v[54:57], v[150:153], v[198:201], v[54:57]
	v_mfma_f32_16x16x32_bf16 v[46:49], v[146:149], v[202:205], v[46:49]
	v_mfma_f32_16x16x32_bf16 v[46:49], v[150:153], v[212:215], v[46:49]
	v_mfma_f32_16x16x32_bf16 v[66:69], v[154:157], v[178:181], v[66:69]
	v_mfma_f32_16x16x32_bf16 v[66:69], v[158:161], v[182:185], v[66:69]
	v_mfma_f32_16x16x32_bf16 v[58:61], v[154:157], v[186:189], v[58:61]
	v_mfma_f32_16x16x32_bf16 v[58:61], v[158:161], v[190:193], v[58:61]
	v_mfma_f32_16x16x32_bf16 v[50:53], v[154:157], v[194:197], v[50:53]
	v_mfma_f32_16x16x32_bf16 v[50:53], v[158:161], v[198:201], v[50:53]
	v_mfma_f32_16x16x32_bf16 v[42:45], v[154:157], v[202:205], v[42:45]
	v_mfma_f32_16x16x32_bf16 v[42:45], v[158:161], v[212:215], v[42:45]
	s_setprio 0
	s_barrier
	s_mov_b64 s[4:5], s[10:11]
	v_mov_b32_e32 v211, v162
	s_add_i32 s56, s56, s17
	ds_read_b128 v[178:181], v210 offset:16384
	ds_read_b128 v[182:185], v210 offset:17408
	ds_read_b128 v[186:189], v210 offset:18432
	ds_read_b128 v[190:193], v210 offset:19456
	ds_read_b128 v[194:197], v210 offset:20480
	ds_read_b128 v[198:201], v210 offset:21504
	ds_read_b128 v[202:205], v210 offset:22528
	ds_read_b128 v[212:215], v210 offset:23552
	s_mov_b32 m0, s56
	s_nop 0
	global_load_lds_dwordx4 v211, s[4:5]
	v_mov_b32_e32 v211, v206
	s_add_i32 m0, s56, 0x2000
	s_nop 0
	global_load_lds_dwordx4 v211, s[4:5]
	s_add_u32 s4, s10, 0x80000
	s_addc_u32 s5, s11, 0
	v_mov_b32_e32 v211, v162
	s_add_i32 s56, s57, s17
	s_mov_b32 m0, s56
	s_nop 0
	global_load_lds_dwordx4 v211, s[4:5]
	v_mov_b32_e32 v211, v206
	s_add_i32 m0, s56, 0x2000
	s_nop 0
	global_load_lds_dwordx4 v211, s[4:5]
	s_mov_b64 s[4:5], s[12:13]
	v_mov_b32_e32 v211, v1
	s_mov_b32 m0, s18
	s_nop 0
	global_load_lds_dwordx4 v211, s[4:5]
	v_mov_b32_e32 v211, v164
	s_mov_b32 m0, s19
	s_nop 0
	global_load_lds_dwordx4 v211, s[4:5]
	s_waitcnt vmcnt(8)
	s_waitcnt lgkmcnt(0)
	s_barrier
; #define PG8_STAGE(bufoff, gbase, voff) do { const char* gb_ = (const char*)(gbase); asm volatile("" : "+s"(gb_)); _Pragma("unroll") for (int _i = 0; _i < 2; ++_i) { unsigned vo_ = (voff)[_i]; asm volatile("" : "+v"(vo_));        \
;         __builtin_amdgcn_global_load_lds((const unsigned*)(gb_ + vo_), (PG8_LAS unsigned*)(lds + (bufoff) + ldsw + _i * 8192), 16, 0, 0); } } while (0)
; #define PG8_LDA(dst, b, h) do { _Pragma("unroll") for (int m = 0; m < 4; ++m) _Pragma("unroll") for (int k = 0; k < 2; ++k) dst[m][k] = *(const PG8_LAS bf16x8*)(lds + PG8_SA(b, h) + aoff + m * 2048 + k * 1024); } while (0)
; #define PG8_LDB(dst, b, h) do { _Pragma("unroll") for (int n = 0; n < 2; ++n) _Pragma("unroll") for (int k = 0; k < 2; ++k) dst[n][k] = *(const PG8_LAS bf16x8*)(lds + PG8_SB(b, h) + boff + n * 2048 + k * 1024); } while (0)
; #define PG8_MMA(ai, bj, At, Bt) do { __builtin_amdgcn_s_setprio(1); _Pragma("unroll") for (int m = 0; m < 4; ++m) _Pragma("unroll") for (int n = 0; n < 2; ++n) _Pragma("unroll") for (int k = 0; k < 2; ++k) \
;         acc[ai][bj][m][n] = __builtin_amdgcn_mfma_f32_16x16x32_bf16(Bt[n][k], At[m][k], acc[ai][bj][m][n], 0, 0, 0); __builtin_amdgcn_s_setprio(0); } while (0)
; #define PG8_WAIT_V(n) asm volatile("s_waitcnt vmcnt(" #n ")" ::: "memory")
; #define PG8_WAIT_L(n) asm volatile("s_waitcnt lgkmcnt(" #n ")" ::: "memory")
; #define PG8_BAR __builtin_amdgcn_s_barrier()
; #define PG8_SCHED __builtin_amdgcn_sched_barrier(0)
; template <class Epi, class Sched, bool ALIGN_EPI = false, bool SP2 = false>
; __device__ __forceinline__ void gemm_phase(PG8_LAS unsigned char* lds, const Gemm g, const Sched& S, const Epi& E) {
;     ...
;             PG8_WAIT_V(8); PG8_WAIT_L(0); PG8_BAR; PG8_MMA(1, 0, At, B0); PG8_MMA(1, 1, At, B1); PG8_BAR; PG8_SCHED;
;             PG8_LDB(B0, 1, 0); PG8_LDB(B1, 1, 1); PG8_SCHED; PG8_LDA(At, 1, 0); PG8_STAGE(PG8_SA(0, 1), a2 + hstep, voffA);
;             PG8_WAIT_V(8); PG8_WAIT_L(0); PG8_BAR; PG8_MMA(0, 0, At, B0); PG8_MMA(0, 1, At, B1); PG8_BAR; PG8_SCHED;
;             PG8_LDA(At, 1, 1); PG8_STAGE(PG8_SB(1, 0), b3, voffB); PG8_STAGE(PG8_SB(1, 1), b3 + hstep, voffB); PG8_STAGE(PG8_SA(1, 0), a3, voffA);
	s_setprio 1
	s_waitcnt lgkmcnt(0)
	v_mfma_f32_16x16x32_bf16 v[110:113], v[26:29], v[178:181], v[110:113]
	v_mfma_f32_16x16x32_bf16 v[106:109], v[98:101], v[178:181], v[106:109]
	v_mfma_f32_16x16x32_bf16 v[94:97], v[26:29], v[186:189], v[94:97]
	v_mfma_f32_16x16x32_bf16 v[90:93], v[98:101], v[186:189], v[90:93]
	v_mfma_f32_16x16x32_bf16 v[86:89], v[26:29], v[194:197], v[86:89]
	v_mfma_f32_16x16x32_bf16 v[82:85], v[98:101], v[194:197], v[82:85]
	v_mfma_f32_16x16x32_bf16 v[26:29], v[26:29], v[202:205], v[78:81]
	v_mfma_f32_16x16x32_bf16 v[110:113], v[30:33], v[182:185], v[110:113]
	v_mfma_f32_16x16x32_bf16 v[106:109], v[102:105], v[182:185], v[106:109]
	v_mfma_f32_16x16x32_bf16 v[94:97], v[30:33], v[190:193], v[94:97]
	v_mfma_f32_16x16x32_bf16 v[90:93], v[102:105], v[190:193], v[90:93]
	v_mfma_f32_16x16x32_bf16 v[86:89], v[30:33], v[198:201], v[86:89]
	v_mfma_f32_16x16x32_bf16 v[82:85], v[102:105], v[198:201], v[82:85]
	v_mfma_f32_16x16x32_bf16 v[26:29], v[30:33], v[212:215], v[26:29]
	v_mfma_f32_16x16x32_bf16 v[30:33], v[98:101], v[202:205], v[74:77]
	v_mfma_f32_16x16x32_bf16 v[30:33], v[102:105], v[212:215], v[30:33]
	s_setprio 0
	s_setprio 1
	v_mfma_f32_16x16x32_bf16 v[38:41], v[146:149], v[178:181], v[38:41]
	v_mfma_f32_16x16x32_bf16 v[38:41], v[150:153], v[182:185], v[38:41]
	v_mfma_f32_16x16x32_bf16 v[22:25], v[146:149], v[186:189], v[22:25]
	v_mfma_f32_16x16x32_bf16 v[22:25], v[150:153], v[190:193], v[22:25]
	v_mfma_f32_16x16x32_bf16 v[14:17], v[146:149], v[194:197], v[14:17]
	v_mfma_f32_16x16x32_bf16 v[14:17], v[150:153], v[198:201], v[14:17]
	v_mfma_f32_16x16x32_bf16 v[6:9], v[146:149], v[202:205], v[6:9]
	v_mfma_f32_16x16x32_bf16 v[6:9], v[150:153], v[212:215], v[6:9]
	v_mfma_f32_16x16x32_bf16 v[34:37], v[154:157], v[178:181], v[34:37]
	v_mfma_f32_16x16x32_bf16 v[34:37], v[158:161], v[182:185], v[34:37]
	v_mfma_f32_16x16x32_bf16 v[18:21], v[154:157], v[186:189], v[18:21]
	v_mfma_f32_16x16x32_bf16 v[18:21], v[158:161], v[190:193], v[18:21]
	v_mfma_f32_16x16x32_bf16 v[10:13], v[154:157], v[194:197], v[10:13]
	v_mfma_f32_16x16x32_bf16 v[10:13], v[158:161], v[198:201], v[10:13]
	v_mfma_f32_16x16x32_bf16 v[2:5], v[154:157], v[202:205], v[2:5]
	v_mfma_f32_16x16x32_bf16 v[2:5], v[158:161], v[212:215], v[2:5]
	s_setprio 0
	s_barrier
	s_add_i32 s56, 0, 0x18000
	s_add_i32 s57, 0, 0x1c000
	v_add_u32_e32 v102, s56, v208
	v_add_u32_e32 v158, s57, v208
	ds_read_b128 v[74:77], v102
	ds_read_b128 v[78:81], v102 offset:1024
	ds_read_b128 v[98:101], v102 offset:2048
	ds_read_b128 v[102:105], v102 offset:3072
	ds_read_b128 v[146:149], v158
	ds_read_b128 v[150:153], v158 offset:1024
	ds_read_b128 v[154:157], v158 offset:2048
	ds_read_b128 v[158:161], v158 offset:3072
	s_add_u32 s4, s12, 0x80000
	s_addc_u32 s5, s13, 0
	v_mov_b32_e32 v211, v1
	s_mov_b32 m0, s20
	ds_read_b128 v[178:181], v210 offset:32768
	ds_read_b128 v[182:185], v210 offset:33792
	ds_read_b128 v[186:189], v210 offset:34816
	ds_read_b128 v[190:193], v210 offset:35840
	ds_read_b128 v[194:197], v210 offset:36864
	ds_read_b128 v[198:201], v210 offset:37888
	ds_read_b128 v[202:205], v210 offset:38912
	ds_read_b128 v[212:215], v210 offset:39936
	s_nop 0
	global_load_lds_dwordx4 v211, s[4:5]
	v_mov_b32_e32 v211, v164
	s_mov_b32 m0, s21
	s_nop 0
	global_load_lds_dwordx4 v211, s[4:5]
	s_waitcnt vmcnt(8)
	s_waitcnt lgkmcnt(0)
	s_barrier
	s_setprio 1
	s_waitcnt lgkmcnt(0)
	v_mfma_f32_16x16x32_bf16 v[142:145], v[74:77], v[178:181], v[142:145]
	v_mfma_f32_16x16x32_bf16 v[142:145], v[78:81], v[182:185], v[142:145]
	v_mfma_f32_16x16x32_bf16 v[134:137], v[74:77], v[186:189], v[134:137]
	v_mfma_f32_16x16x32_bf16 v[134:137], v[78:81], v[190:193], v[134:137]
	v_mfma_f32_16x16x32_bf16 v[126:129], v[74:77], v[194:197], v[126:129]
	v_mfma_f32_16x16x32_bf16 v[126:129], v[78:81], v[198:201], v[126:129]
	v_mfma_f32_16x16x32_bf16 v[118:121], v[74:77], v[202:205], v[118:121]
	v_mfma_f32_16x16x32_bf16 v[118:121], v[78:81], v[212:215], v[118:121]
	v_mfma_f32_16x16x32_bf16 v[138:141], v[98:101], v[178:181], v[138:141]
	v_mfma_f32_16x16x32_bf16 v[138:141], v[102:105], v[182:185], v[138:141]
	v_mfma_f32_16x16x32_bf16 v[130:133], v[98:101], v[186:189], v[130:133]
	v_mfma_f32_16x16x32_bf16 v[130:133], v[102:105], v[190:193], v[130:133]
	v_mfma_f32_16x16x32_bf16 v[122:125], v[98:101], v[194:197], v[122:125]
	v_mfma_f32_16x16x32_bf16 v[122:125], v[102:105], v[198:201], v[122:125]
	v_mfma_f32_16x16x32_bf16 v[114:117], v[98:101], v[202:205], v[114:117]
	v_mfma_f32_16x16x32_bf16 v[114:117], v[102:105], v[212:215], v[114:117]
	s_setprio 0
	s_setprio 1
	v_mfma_f32_16x16x32_bf16 v[70:73], v[146:149], v[178:181], v[70:73]
	v_mfma_f32_16x16x32_bf16 v[70:73], v[150:153], v[182:185], v[70:73]
	v_mfma_f32_16x16x32_bf16 v[62:65], v[146:149], v[186:189], v[62:65]
	v_mfma_f32_16x16x32_bf16 v[62:65], v[150:153], v[190:193], v[62:65]
	v_mfma_f32_16x16x32_bf16 v[54:57], v[146:149], v[194:197], v[54:57]
	v_mfma_f32_16x16x32_bf16 v[54:57], v[150:153], v[198:201], v[54:57]
	v_mfma_f32_16x16x32_bf16 v[46:49], v[146:149], v[202:205], v[46:49]
	v_mfma_f32_16x16x32_bf16 v[46:49], v[150:153], v[212:215], v[46:49]
	v_mfma_f32_16x16x32_bf16 v[66:69], v[154:157], v[178:181], v[66:69]
	v_mfma_f32_16x16x32_bf16 v[66:69], v[158:161], v[182:185], v[66:69]
	v_mfma_f32_16x16x32_bf16 v[58:61], v[154:157], v[186:189], v[58:61]
	v_mfma_f32_16x16x32_bf16 v[58:61], v[158:161], v[190:193], v[58:61]
	v_mfma_f32_16x16x32_bf16 v[50:53], v[154:157], v[194:197], v[50:53]
	v_mfma_f32_16x16x32_bf16 v[50:53], v[158:161], v[198:201], v[50:53]
	v_mfma_f32_16x16x32_bf16 v[42:45], v[154:157], v[202:205], v[42:45]
	v_mfma_f32_16x16x32_bf16 v[42:45], v[158:161], v[212:215], v[42:45]
	s_setprio 0
	s_barrier
;     __device__ __forceinline__ void operator()(const f32x4 (&acc)[2][2][4][2], const Unit& u, int wr, int wc, int fr, int fq) const {
;         const int row0 = u.pm * BM + wr * 64 + fr, col0 = u.pn * BM + wc * 32 + 8 * fq, b = (u.pm * BM) / rows_per_batch;
;         const float* g = gate + (size_t)b * gate_bstride + col0;
;         float ssq[2][4];
; #pragma unroll
;         for (int ai = 0; ai < 2; ++ai)
; #pragma unroll
;             for (int m = 0; m < 4; ++m) ssq[ai][m] = 0.f;
;         f32x4 gv[2][2], Gv[2][2];
; #pragma unroll
;         for (int bj = 0; bj < 2; ++bj) { gv[bj][0] = *(const f32x4*)(g + bj * HALF); gv[bj][1] = *(const f32x4*)(g + bj * HALF + 4); Gv[bj][0] = (f32x4){0.f, 0.f, 0.f, 0.f}; Gv[bj][1] = (f32x4){0.f, 0.f, 0.f, 0.f};
;             if (Hn) { const float* sc = scnext + (size_t)b * gate_bstride + col0 + bj * HALF;
;                 Gv[bj][0] = *(const f32x4*)(gnext + col0 + bj * HALF) * (1.0f + *(const f32x4*)(sc)); Gv[bj][1] = *(const f32x4*)(gnext + col0 + bj * HALF + 4) * (1.0f + *(const f32x4*)(sc + 4)); } }
; #pragma unroll
;         for (int bj = 0; bj < 2; ++bj) {
;             const f32x4 g0 = gv[bj][0], g1 = gv[bj][1], G0 = Gv[bj][0], G1 = Gv[bj][1];
; #pragma unroll
;             for (int ai = 0; ai < 2; ++ai)
; #pragma unroll
;                 for (int m = 0; m < 4; ++m) { const size_t off = (size_t)(row0 + ai * HALF + m * 16) * 2048 + col0 + bj * HALF;
;                     f32x4 x0 = __builtin_nontemporal_load((const f32x4*)(base + off)), x1 = __builtin_nontemporal_load((const f32x4*)(base + off + 4));
;                     if constexpr (HAS_DIN) { const u32x4 dw = __builtin_nontemporal_load((const u32x4*)(dbuf + off));
;                         x0 += (f32x4){__builtin_bit_cast(float, dw.x << 16), __builtin_bit_cast(float, dw.x & 0xffff0000u), __builtin_bit_cast(float, dw.y << 16), __builtin_bit_cast(float, dw.y & 0xffff0000u)};
; template <class Epi, class Sched, bool ALIGN_EPI = false, bool SP2 = false>
; __device__ __forceinline__ void gemm_phase(PG8_LAS unsigned char* lds, const Gemm g, const Sched& S, const Epi& E) {
;     ...
;             PG8_LDA(At, 1, 1); PG8_STAGE(PG8_SB(1, 0), b3, voffB); PG8_STAGE(PG8_SB(1, 1), b3 + hstep, voffB); PG8_STAGE(PG8_SA(1, 0), a3, voffA);
;             PG8_WAIT_V(8); PG8_WAIT_L(0); PG8_BAR; PG8_MMA(1, 0, At, B0); PG8_MMA(1, 1, At, B1); PG8_BAR; PG8_SCHED;
	s_add_u32 s4, s10, 0x80
	s_addc_u32 s5, s11, 0
	v_mov_b32_e32 v211, v162
	s_add_i32 s12, s56, s17
	ds_read_b128 v[178:181], v210 offset:49152
	ds_read_b128 v[182:185], v210 offset:50176
	ds_read_b128 v[186:189], v210 offset:51200
	ds_read_b128 v[190:193], v210 offset:52224
	ds_read_b128 v[194:197], v210 offset:53248
	ds_read_b128 v[198:201], v210 offset:54272
	ds_read_b128 v[202:205], v210 offset:55296
	ds_read_b128 v[212:215], v210 offset:56320
	s_mov_b32 m0, s12
	s_nop 0
	global_load_lds_dwordx4 v211, s[4:5]
	v_mov_b32_e32 v211, v206
	s_add_i32 m0, s12, 0x2000
	s_nop 0
	global_load_lds_dwordx4 v211, s[4:5]
	s_add_u32 s4, s10, 0x80080
	s_addc_u32 s5, s11, 0
	v_mov_b32_e32 v211, v162
	s_add_i32 s10, s57, s17
	s_mov_b32 m0, s10
	s_nop 0
	global_load_lds_dwordx4 v211, s[4:5]
	v_mov_b32_e32 v211, v206
	s_add_i32 m0, s10, 0x2000
	s_nop 0
	global_load_lds_dwordx4 v211, s[4:5]
	v_mov_b32_e32 v211, v1
	s_mov_b32 m0, s26
	s_nop 0
	global_load_lds_dwordx4 v211, s[8:9]
	v_mov_b32_e32 v211, v164
	s_mov_b32 m0, s27
	s_nop 0
	global_load_lds_dwordx4 v211, s[8:9]
	s_waitcnt vmcnt(8)
	s_waitcnt lgkmcnt(0)
	s_barrier
	s_setprio 1
	s_waitcnt lgkmcnt(0)
	v_mfma_f32_16x16x32_bf16 v[110:113], v[74:77], v[178:181], v[110:113]
	v_mfma_f32_16x16x32_bf16 v[94:97], v[74:77], v[186:189], v[94:97]
	v_mfma_f32_16x16x32_bf16 v[86:89], v[74:77], v[194:197], v[86:89]
	v_mfma_f32_16x16x32_bf16 v[26:29], v[74:77], v[202:205], v[26:29]
	v_mfma_f32_16x16x32_bf16 v[110:113], v[78:81], v[182:185], v[110:113]
	v_mfma_f32_16x16x32_bf16 v[106:109], v[98:101], v[178:181], v[106:109]
	v_mfma_f32_16x16x32_bf16 v[94:97], v[78:81], v[190:193], v[94:97]
	v_mfma_f32_16x16x32_bf16 v[90:93], v[98:101], v[186:189], v[90:93]
	v_mfma_f32_16x16x32_bf16 v[86:89], v[78:81], v[198:201], v[86:89]
	v_mfma_f32_16x16x32_bf16 v[82:85], v[98:101], v[194:197], v[82:85]
	v_mfma_f32_16x16x32_bf16 v[78:81], v[78:81], v[212:215], v[26:29]
	v_mfma_f32_16x16x32_bf16 v[26:29], v[98:101], v[202:205], v[30:33]
	v_mfma_f32_16x16x32_bf16 v[106:109], v[102:105], v[182:185], v[106:109]
	v_mfma_f32_16x16x32_bf16 v[90:93], v[102:105], v[190:193], v[90:93]
	v_mfma_f32_16x16x32_bf16 v[82:85], v[102:105], v[198:201], v[82:85]
	v_mfma_f32_16x16x32_bf16 v[74:77], v[102:105], v[212:215], v[26:29]
	s_setprio 0
	s_setprio 1
	v_mfma_f32_16x16x32_bf16 v[26:29], v[146:149], v[178:181], v[38:41]
	v_mfma_f32_16x16x32_bf16 v[38:41], v[150:153], v[182:185], v[26:29]
	v_mfma_f32_16x16x32_bf16 v[26:29], v[154:157], v[178:181], v[34:37]
	v_mfma_f32_16x16x32_bf16 v[22:25], v[146:149], v[186:189], v[22:25]
	v_mfma_f32_16x16x32_bf16 v[18:21], v[154:157], v[186:189], v[18:21]
	v_mfma_f32_16x16x32_bf16 v[14:17], v[146:149], v[194:197], v[14:17]
	v_mfma_f32_16x16x32_bf16 v[10:13], v[154:157], v[194:197], v[10:13]
	v_mfma_f32_16x16x32_bf16 v[6:9], v[146:149], v[202:205], v[6:9]
	v_mfma_f32_16x16x32_bf16 v[2:5], v[154:157], v[202:205], v[2:5]
	v_mfma_f32_16x16x32_bf16 v[34:37], v[158:161], v[182:185], v[26:29]
	v_mfma_f32_16x16x32_bf16 v[22:25], v[150:153], v[190:193], v[22:25]
	v_mfma_f32_16x16x32_bf16 v[18:21], v[158:161], v[190:193], v[18:21]
	v_mfma_f32_16x16x32_bf16 v[14:17], v[150:153], v[198:201], v[14:17]
	v_mfma_f32_16x16x32_bf16 v[10:13], v[158:161], v[198:201], v[10:13]
	v_mfma_f32_16x16x32_bf16 v[6:9], v[150:153], v[212:215], v[6:9]
	v_mfma_f32_16x16x32_bf16 v[2:5], v[158:161], v[212:215], v[2:5]
	s_setprio 0
	s_barrier
	s_add_i32 s51, s51, 2
	s_add_u32 s40, s40, 0x100
	s_addc_u32 s49, s49, 0
	s_cmp_gt_u32 s51, 29
	s_mov_b64 s[4:5], s[6:7]
	s_cbranch_scc0 .LBB0_555
	s_ashr_i32 s4, s29, 31
	s_lshr_b32 s4, s4, 27
	s_add_i32 s4, s29, s4
	s_ashr_i32 s4, s4, 5
	v_lshl_or_b32 v148, s33, 8, v209
	s_mul_i32 s7, s4, 0xc000
	v_ashrrev_i32_e32 v149, 31, v148
	s_mul_hi_i32 s6, s4, 0xc000
	s_add_u32 s4, s22, s7
	s_addc_u32 s5, s23, s6
	v_lshlrev_b64 v[26:27], 2, v[148:149]
	v_lshl_add_u64 v[146:147], s[4:5], 0, v[26:27]
	s_add_u32 s4, s24, s7
	s_addc_u32 s5, s25, s6
	v_lshl_add_u64 v[160:161], s[4:5], 0, v[26:27]
	v_lshl_add_u64 v[178:179], s[46:47], 0, v[26:27]
	global_load_dwordx4 v[98:101], v[146:147], off offset:16
	global_load_dwordx4 v[102:105], v[146:147], off
	global_load_dwordx4 v[26:29], v[178:179], off offset:16
	global_load_dwordx4 v[30:33], v[178:179], off
	global_load_dwordx4 v[150:153], v[160:161], off offset:16
	global_load_dwordx4 v[154:157], v[160:161], off
	s_mov_b64 s[4:5], 0x40000
	s_waitcnt vmcnt(0)
	v_pk_mul_f32 v[188:189], v[140:141], v[100:101]
	v_pk_mul_f32 v[142:143], v[142:143], v[102:103]
	v_pk_mul_f32 v[144:145], v[144:145], v[104:105]
	v_pk_mul_f32 v[140:141], v[138:139], v[98:99]
	v_pk_mul_f32 v[136:137], v[136:137], v[104:105]
	v_pk_add_f32 v[156:157], v[156:157], 1.0 op_sel_hi:[1,0]
	v_pk_add_f32 v[154:155], v[154:155], 1.0 op_sel_hi:[1,0]
	v_pk_mul_f32 v[198:199], v[32:33], v[156:157]
	v_pk_mul_f32 v[200:201], v[30:31], v[154:155]
	v_pk_add_f32 v[30:31], v[152:153], 1.0 op_sel_hi:[1,0]
	v_pk_add_f32 v[32:33], v[150:151], 1.0 op_sel_hi:[1,0]
	v_pk_mul_f32 v[202:203], v[28:29], v[30:31]
	v_pk_mul_f32 v[204:205], v[26:27], v[32:33]
	global_load_dwordx4 v[26:29], v[146:147], off offset:528
	global_load_dwordx4 v[30:33], v[146:147], off offset:512
	global_load_dwordx4 v[156:159], v[178:179], off offset:528
	global_load_dwordx4 v[152:155], v[178:179], off offset:512
	s_nop 0
	global_load_dwordx4 v[178:181], v[160:161], off offset:528
	global_load_dwordx4 v[182:185], v[160:161], off offset:512
	v_pk_mul_f32 v[134:135], v[134:135], v[102:103]
	v_pk_mul_f32 v[130:131], v[130:131], v[98:99]
	v_pk_mul_f32 v[132:133], v[132:133], v[100:101]
	v_pk_mul_f32 v[128:129], v[128:129], v[104:105]
	v_pk_mul_f32 v[126:127], v[126:127], v[102:103]
	v_pk_mul_f32 v[122:123], v[122:123], v[98:99]
	v_pk_mul_f32 v[124:125], v[124:125], v[100:101]
	v_pk_mul_f32 v[120:121], v[120:121], v[104:105]
	v_pk_mul_f32 v[118:119], v[118:119], v[102:103]
	v_pk_mul_f32 v[114:115], v[114:115], v[98:99]
	v_pk_mul_f32 v[116:117], v[116:117], v[100:101]
	v_pk_mul_f32 v[112:113], v[112:113], v[104:105]
	v_pk_mul_f32 v[110:111], v[110:111], v[102:103]
	v_pk_mul_f32 v[106:107], v[106:107], v[98:99]
	v_pk_mul_f32 v[108:109], v[108:109], v[100:101]
	v_pk_mul_f32 v[96:97], v[96:97], v[104:105]
	v_pk_mul_f32 v[94:95], v[94:95], v[102:103]
	v_pk_mul_f32 v[90:91], v[90:91], v[98:99]
	v_pk_mul_f32 v[92:93], v[92:93], v[100:101]
	v_pk_mul_f32 v[88:89], v[88:89], v[104:105]
	v_pk_mul_f32 v[86:87], v[86:87], v[102:103]
	v_pk_mul_f32 v[82:83], v[82:83], v[98:99]
	v_pk_mul_f32 v[84:85], v[84:85], v[100:101]
	v_pk_mul_f32 v[80:81], v[80:81], v[104:105]
	v_pk_mul_f32 v[78:79], v[78:79], v[102:103]
	v_pk_mul_f32 v[74:75], v[74:75], v[98:99]
	v_pk_mul_f32 v[76:77], v[76:77], v[100:101]
	s_waitcnt vmcnt(5)
; __device__ __forceinline__ unsigned cvt_pk_bf16(float lo, float hi) { unsigned r; asm volatile("v_cvt_pk_bf16_f32 %0, %1, %2" : "=v"(r) : "v"(lo), "v"(hi)); return r; }
;     __device__ __forceinline__ void operator()(const f32x4 (&acc)[2][2][4][2], const Unit& u, int wr, int wc, int fr, int fq) const {
;     ...
;                 for (int m = 0; m < 4; ++m) { const size_t off = (size_t)(row0 + ai * HALF + m * 16) * 2048 + col0 + bj * HALF;
;                     f32x4 x0 = __builtin_nontemporal_load((const f32x4*)(base + off)), x1 = __builtin_nontemporal_load((const f32x4*)(base + off + 4));
;                     if constexpr (HAS_DIN) { const u32x4 dw = __builtin_nontemporal_load((const u32x4*)(dbuf + off));
;                         x0 += (f32x4){__builtin_bit_cast(float, dw.x << 16), __builtin_bit_cast(float, dw.x & 0xffff0000u), __builtin_bit_cast(float, dw.y << 16), __builtin_bit_cast(float, dw.y & 0xffff0000u)};
;                         x1 += (f32x4){__builtin_bit_cast(float, dw.z << 16), __builtin_bit_cast(float, dw.z & 0xffff0000u), __builtin_bit_cast(float, dw.w << 16), __builtin_bit_cast(float, dw.w & 0xffff0000u)}; }
;                     f32x4 o0, o1;
;                     if constexpr (OUT_DELTA) { const f32x4 d0 = g0 * acc[ai][bj][m][0], d1 = g1 * acc[ai][bj][m][1];
;                         u32x4 w; w.x = cvt_pk_bf16(d0[0], d0[1]); w.y = cvt_pk_bf16(d0[2], d0[3]); w.z = cvt_pk_bf16(d1[0], d1[1]); w.w = cvt_pk_bf16(d1[2], d1[3]);
;                         *(u32x4*)(dbuf + off) = w;
;                         o0 = x0 + (f32x4){__builtin_bit_cast(float, w.x << 16), __builtin_bit_cast(float, w.x & 0xffff0000u), __builtin_bit_cast(float, w.y << 16), __builtin_bit_cast(float, w.y & 0xffff0000u)};
;                         o1 = x1 + (f32x4){__builtin_bit_cast(float, w.z << 16), __builtin_bit_cast(float, w.z & 0xffff0000u), __builtin_bit_cast(float, w.w << 16), __builtin_bit_cast(float, w.w & 0xffff0000u)}; }
;                     else { o0 = x0 + g0 * acc[ai][bj][m][0]; o1 = x1 + g1 * acc[ai][bj][m][1]; *(f32x4*)(out + off) = o0; *(f32x4*)(out + off + 4) = o1; }
;                     if (Hn) { const f32x4 h0 = o0 * G0, h1 = o1 * G1;
;                         u32x4 w; w.x = cvt_pk_bf16(h0[0], h0[1]); w.y = cvt_pk_bf16(h0[2], h0[3]); w.z = cvt_pk_bf16(h1[0], h1[1]); w.w = cvt_pk_bf16(h1[2], h1[3]);
;                         *(u32x4*)(Hn + off) = w;
	v_pk_mul_f32 v[58:59], v[58:59], v[26:27]
	s_waitcnt vmcnt(4)
	v_pk_mul_f32 v[72:73], v[72:73], v[32:33]
	v_pk_mul_f32 v[70:71], v[70:71], v[30:31]
	v_pk_mul_f32 v[64:65], v[64:65], v[32:33]
	v_pk_mul_f32 v[62:63], v[62:63], v[30:31]
	s_waitcnt vmcnt(0)
	v_pk_add_f32 v[146:147], v[184:185], 1.0 op_sel_hi:[1,0]
	v_pk_add_f32 v[160:161], v[182:183], 1.0 op_sel_hi:[1,0]
	v_pk_mul_f32 v[150:151], v[154:155], v[146:147]
	v_pk_add_f32 v[146:147], v[180:181], 1.0 op_sel_hi:[1,0]
	v_pk_mul_f32 v[152:153], v[152:153], v[160:161]
	v_pk_mul_f32 v[154:155], v[158:159], v[146:147]
	v_lshl_add_u32 v146, s29, 8, v207
	v_ashrrev_i32_e32 v147, 31, v146
	v_lshlrev_b64 v[184:185], 11, v[146:147]
	v_lshl_add_u64 v[186:187], v[184:185], 0, v[148:149]
	v_pk_add_f32 v[160:161], v[178:179], 1.0 op_sel_hi:[1,0]
	v_lshl_add_u64 v[178:179], v[186:187], 2, s[44:45]
	v_pk_mul_f32 v[156:157], v[156:157], v[160:161]
	global_load_dwordx4 v[158:161], v[178:179], off nt
	global_load_dwordx4 v[180:183], v[178:179], off offset:16 nt
	v_cvt_pk_bf16_f32 v138, v142, v143
	v_lshlrev_b64 v[142:143], 1, v[186:187]
	v_cvt_pk_bf16_f32 v139, v144, v145
	v_cvt_pk_bf16_f32 v140, v140, v141
	v_cvt_pk_bf16_f32 v141, v188, v189
	v_lshl_add_u64 v[144:145], s[90:91], 0, v[142:143]
	global_store_dwordx4 v[144:145], v[138:141], off
	v_lshlrev_b32_e32 v144, 16, v140
	v_and_b32_e32 v145, 0xffff0000, v140
	v_lshlrev_b32_e32 v140, 16, v141
	v_and_b32_e32 v141, 0xffff0000, v141
	v_lshl_add_u64 v[142:143], s[96:97], 0, v[142:143]
	v_pk_mul_f32 v[60:61], v[60:61], v[28:29]
	v_pk_mul_f32 v[56:57], v[56:57], v[32:33]
	v_pk_mul_f32 v[54:55], v[54:55], v[30:31]
	v_pk_mul_f32 v[50:51], v[50:51], v[26:27]
	v_pk_mul_f32 v[52:53], v[52:53], v[28:29]
	v_pk_mul_f32 v[48:49], v[48:49], v[32:33]
	v_pk_mul_f32 v[46:47], v[46:47], v[30:31]
	v_pk_mul_f32 v[42:43], v[42:43], v[26:27]
	v_pk_mul_f32 v[44:45], v[44:45], v[28:29]
	v_pk_mul_f32 v[40:41], v[40:41], v[32:33]
	v_pk_mul_f32 v[38:39], v[38:39], v[30:31]
	v_pk_mul_f32 v[34:35], v[34:35], v[26:27]
	v_pk_mul_f32 v[36:37], v[36:37], v[28:29]
	v_pk_mul_f32 v[24:25], v[24:25], v[32:33]
	v_pk_mul_f32 v[22:23], v[22:23], v[30:31]
	v_pk_mul_f32 v[18:19], v[18:19], v[26:27]
	v_pk_mul_f32 v[20:21], v[20:21], v[28:29]
	v_pk_mul_f32 v[16:17], v[16:17], v[32:33]
	v_pk_mul_f32 v[14:15], v[14:15], v[30:31]
	v_pk_mul_f32 v[10:11], v[10:11], v[26:27]
	v_pk_mul_f32 v[12:13], v[12:13], v[28:29]
	v_pk_mul_f32 v[8:9], v[8:9], v[32:33]
	v_pk_mul_f32 v[6:7], v[6:7], v[30:31]
	v_pk_mul_f32 v[2:3], v[2:3], v[26:27]
	v_pk_mul_f32 v[4:5], v[4:5], v[28:29]
	s_waitcnt vmcnt(1)
	v_pk_add_f32 v[182:183], v[182:183], v[140:141]
	v_lshlrev_b32_e32 v140, 16, v138
	v_and_b32_e32 v141, 0xffff0000, v138
	v_lshlrev_b32_e32 v138, 16, v139
	v_and_b32_e32 v139, 0xffff0000, v139
	v_pk_add_f32 v[158:159], v[158:159], v[140:141]
	v_pk_add_f32 v[160:161], v[160:161], v[138:139]
	v_pk_mul_f32 v[138:139], v[200:201], v[158:159]
	v_pk_add_f32 v[144:145], v[180:181], v[144:145]
	v_pk_mul_f32 v[140:141], v[198:199], v[160:161]
	v_cvt_pk_bf16_f32 v138, v138, v139
	v_pk_mul_f32 v[180:181], v[202:203], v[182:183]
	v_cvt_pk_bf16_f32 v139, v140, v141
	v_pk_mul_f32 v[186:187], v[204:205], v[144:145]
	s_nop 0
	v_cvt_pk_bf16_f32 v140, v186, v187
	v_cvt_pk_bf16_f32 v141, v180, v181
	global_store_dwordx4 v[142:143], v[138:141], off
	s_nop 1
	v_mul_f32_e32 v138, v159, v159
	v_mul_f32_e32 v139, v161, v161
	v_fmac_f32_e32 v138, v158, v158
	v_fmac_f32_e32 v139, v160, v160
	v_add_f32_e32 v138, v138, v139
	v_mul_f32_e32 v139, v145, v145
	v_mul_f32_e32 v140, v183, v183
	v_fmac_f32_e32 v139, v144, v144
	v_fmac_f32_e32 v140, v182, v182
	v_add_f32_e32 v139, v139, v140
	v_add_f32_e32 v211, v138, v139
	v_or_b32_e32 v138, 16, v146
	v_ashrrev_i32_e32 v139, 31, v138
	v_lshlrev_b64 v[140:141], 11, v[138:139]
	v_lshl_add_u64 v[180:181], v[140:141], 0, v[148:149]
	v_lshl_add_u64 v[138:139], v[180:181], 2, s[44:45]
	global_load_dwordx4 v[142:145], v[138:139], off nt
	global_load_dwordx4 v[158:161], v[138:139], off offset:16 nt
	v_lshlrev_b64 v[180:181], 1, v[180:181]
	v_cvt_pk_bf16_f32 v134, v134, v135
	v_cvt_pk_bf16_f32 v135, v136, v137
	v_cvt_pk_bf16_f32 v136, v130, v131
	v_cvt_pk_bf16_f32 v137, v132, v133
	v_lshl_add_u64 v[130:131], s[90:91], 0, v[180:181]
	global_store_dwordx4 v[130:131], v[134:137], off
	v_lshlrev_b32_e32 v132, 16, v136
	v_and_b32_e32 v133, 0xffff0000, v136
	v_lshlrev_b32_e32 v130, 16, v137
	v_and_b32_e32 v131, 0xffff0000, v137
	v_lshlrev_b32_e32 v136, 16, v134
	v_and_b32_e32 v137, 0xffff0000, v134
	v_lshlrev_b32_e32 v134, 16, v135
	v_and_b32_e32 v135, 0xffff0000, v135
	s_waitcnt vmcnt(2)
	v_pk_add_f32 v[134:135], v[144:145], v[134:135]
	s_waitcnt vmcnt(1)
	v_pk_add_f32 v[130:131], v[160:161], v[130:131]
	v_pk_add_f32 v[136:137], v[142:143], v[136:137]
	v_pk_add_f32 v[132:133], v[158:159], v[132:133]
	v_pk_mul_f32 v[144:145], v[198:199], v[134:135]
	v_pk_mul_f32 v[142:143], v[200:201], v[136:137]
	v_pk_mul_f32 v[158:159], v[202:203], v[130:131]
	v_pk_mul_f32 v[160:161], v[204:205], v[132:133]
	v_cvt_pk_bf16_f32 v142, v142, v143
	v_cvt_pk_bf16_f32 v143, v144, v145
	s_nop 0
	v_cvt_pk_bf16_f32 v144, v160, v161
	v_cvt_pk_bf16_f32 v145, v158, v159
	v_lshl_add_u64 v[158:159], s[96:97], 0, v[180:181]
	global_store_dwordx4 v[158:159], v[142:145], off
	s_nop 1
	v_or_b32_e32 v142, 32, v146
	v_ashrrev_i32_e32 v143, 31, v142
	v_lshlrev_b64 v[144:145], 11, v[142:143]
	v_lshl_add_u64 v[186:187], v[144:145], 0, v[148:149]
	v_lshl_add_u64 v[142:143], v[186:187], 2, s[44:45]
	global_load_dwordx4 v[158:161], v[142:143], off nt
	global_load_dwordx4 v[180:183], v[142:143], off offset:16 nt
	v_lshlrev_b64 v[186:187], 1, v[186:187]
	v_cvt_pk_bf16_f32 v126, v126, v127
	v_cvt_pk_bf16_f32 v127, v128, v129
	v_cvt_pk_bf16_f32 v128, v122, v123
	v_cvt_pk_bf16_f32 v129, v124, v125
	v_lshl_add_u64 v[122:123], s[90:91], 0, v[186:187]
	global_store_dwordx4 v[122:123], v[126:129], off
	v_lshlrev_b32_e32 v124, 16, v128
	v_and_b32_e32 v125, 0xffff0000, v128
	v_lshlrev_b32_e32 v122, 16, v129
	v_and_b32_e32 v123, 0xffff0000, v129
	v_lshlrev_b32_e32 v128, 16, v126
	v_and_b32_e32 v129, 0xffff0000, v126
	v_lshlrev_b32_e32 v126, 16, v127
	v_and_b32_e32 v127, 0xffff0000, v127
	s_waitcnt vmcnt(2)
; __device__ __forceinline__ unsigned cvt_pk_bf16(float lo, float hi) { unsigned r; asm volatile("v_cvt_pk_bf16_f32 %0, %1, %2" : "=v"(r) : "v"(lo), "v"(hi)); return r; }
;     __device__ __forceinline__ void operator()(const f32x4 (&acc)[2][2][4][2], const Unit& u, int wr, int wc, int fr, int fq) const {
;     ...
;                 for (int m = 0; m < 4; ++m) { const size_t off = (size_t)(row0 + ai * HALF + m * 16) * 2048 + col0 + bj * HALF;
;                     f32x4 x0 = __builtin_nontemporal_load((const f32x4*)(base + off)), x1 = __builtin_nontemporal_load((const f32x4*)(base + off + 4));
;                     if constexpr (HAS_DIN) { const u32x4 dw = __builtin_nontemporal_load((const u32x4*)(dbuf + off));
;                         x0 += (f32x4){__builtin_bit_cast(float, dw.x << 16), __builtin_bit_cast(float, dw.x & 0xffff0000u), __builtin_bit_cast(float, dw.y << 16), __builtin_bit_cast(float, dw.y & 0xffff0000u)};
;                         x1 += (f32x4){__builtin_bit_cast(float, dw.z << 16), __builtin_bit_cast(float, dw.z & 0xffff0000u), __builtin_bit_cast(float, dw.w << 16), __builtin_bit_cast(float, dw.w & 0xffff0000u)}; }
;                     f32x4 o0, o1;
;                     if constexpr (OUT_DELTA) { const f32x4 d0 = g0 * acc[ai][bj][m][0], d1 = g1 * acc[ai][bj][m][1];
;                         u32x4 w; w.x = cvt_pk_bf16(d0[0], d0[1]); w.y = cvt_pk_bf16(d0[2], d0[3]); w.z = cvt_pk_bf16(d1[0], d1[1]); w.w = cvt_pk_bf16(d1[2], d1[3]);
;                         *(u32x4*)(dbuf + off) = w;
;                         o0 = x0 + (f32x4){__builtin_bit_cast(float, w.x << 16), __builtin_bit_cast(float, w.x & 0xffff0000u), __builtin_bit_cast(float, w.y << 16), __builtin_bit_cast(float, w.y & 0xffff0000u)};
;                         o1 = x1 + (f32x4){__builtin_bit_cast(float, w.z << 16), __builtin_bit_cast(float, w.z & 0xffff0000u), __builtin_bit_cast(float, w.w << 16), __builtin_bit_cast(float, w.w & 0xffff0000u)}; }
;                     else { o0 = x0 + g0 * acc[ai][bj][m][0]; o1 = x1 + g1 * acc[ai][bj][m][1]; *(f32x4*)(out + off) = o0; *(f32x4*)(out + off + 4) = o1; }
;                     if (Hn) { const f32x4 h0 = o0 * G0, h1 = o1 * G1;
;                         u32x4 w; w.x = cvt_pk_bf16(h0[0], h0[1]); w.y = cvt_pk_bf16(h0[2], h0[3]); w.z = cvt_pk_bf16(h1[0], h1[1]); w.w = cvt_pk_bf16(h1[2], h1[3]);
;                         *(u32x4*)(Hn + off) = w;
	v_pk_add_f32 v[126:127], v[160:161], v[126:127]
	s_waitcnt vmcnt(1)
	v_pk_add_f32 v[122:123], v[182:183], v[122:123]
	v_pk_add_f32 v[128:129], v[158:159], v[128:129]
	v_pk_add_f32 v[124:125], v[180:181], v[124:125]
	v_pk_mul_f32 v[160:161], v[198:199], v[126:127]
	v_pk_mul_f32 v[158:159], v[200:201], v[128:129]
	v_pk_mul_f32 v[180:181], v[202:203], v[122:123]
	v_pk_mul_f32 v[182:183], v[204:205], v[124:125]
	v_cvt_pk_bf16_f32 v158, v158, v159
	v_cvt_pk_bf16_f32 v159, v160, v161
	s_nop 0
	v_cvt_pk_bf16_f32 v160, v182, v183
	v_cvt_pk_bf16_f32 v161, v180, v181
	v_lshl_add_u64 v[180:181], s[96:97], 0, v[186:187]
	global_store_dwordx4 v[180:181], v[158:161], off
	s_nop 1
	v_or_b32_e32 v158, 48, v146
	v_ashrrev_i32_e32 v159, 31, v158
	v_lshlrev_b64 v[160:161], 11, v[158:159]
	v_lshl_add_u64 v[190:191], v[160:161], 0, v[148:149]
	v_lshl_add_u64 v[158:159], v[190:191], 2, s[44:45]
	global_load_dwordx4 v[180:183], v[158:159], off nt
	global_load_dwordx4 v[186:189], v[158:159], off offset:16 nt
	v_lshlrev_b64 v[190:191], 1, v[190:191]
	v_cvt_pk_bf16_f32 v118, v118, v119
	v_cvt_pk_bf16_f32 v119, v120, v121
	v_cvt_pk_bf16_f32 v120, v114, v115
	v_cvt_pk_bf16_f32 v121, v116, v117
	v_lshl_add_u64 v[114:115], s[90:91], 0, v[190:191]
	global_store_dwordx4 v[114:115], v[118:121], off
	v_lshlrev_b32_e32 v116, 16, v120
	v_and_b32_e32 v117, 0xffff0000, v120
	v_lshlrev_b32_e32 v114, 16, v121
	v_and_b32_e32 v115, 0xffff0000, v121
	v_lshlrev_b32_e32 v120, 16, v118
	v_and_b32_e32 v121, 0xffff0000, v118
	v_lshlrev_b32_e32 v118, 16, v119
	v_and_b32_e32 v119, 0xffff0000, v119
	s_waitcnt vmcnt(2)
	v_pk_add_f32 v[118:119], v[182:183], v[118:119]
	s_waitcnt vmcnt(1)
	v_pk_add_f32 v[114:115], v[188:189], v[114:115]
	v_pk_add_f32 v[120:121], v[180:181], v[120:121]
	v_pk_add_f32 v[116:117], v[186:187], v[116:117]
	v_pk_mul_f32 v[182:183], v[198:199], v[118:119]
	v_pk_mul_f32 v[180:181], v[200:201], v[120:121]
	v_pk_mul_f32 v[186:187], v[202:203], v[114:115]
	v_pk_mul_f32 v[188:189], v[204:205], v[116:117]
	v_cvt_pk_bf16_f32 v180, v180, v181
	v_cvt_pk_bf16_f32 v181, v182, v183
	s_nop 0
	v_cvt_pk_bf16_f32 v182, v188, v189
	v_cvt_pk_bf16_f32 v183, v186, v187
	v_lshl_add_u64 v[186:187], s[96:97], 0, v[190:191]
	global_store_dwordx4 v[186:187], v[180:183], off
	s_nop 1
	v_lshl_add_u64 v[182:183], v[184:185], 0, s[4:5]
	v_lshl_add_u64 v[194:195], v[182:183], 0, v[148:149]
	v_lshl_add_u64 v[180:181], v[194:195], 2, s[44:45]
	global_load_dwordx4 v[186:189], v[180:181], off nt
	global_load_dwordx4 v[190:193], v[180:181], off offset:16 nt
	v_lshlrev_b64 v[194:195], 1, v[194:195]
	v_cvt_pk_bf16_f32 v110, v110, v111
	v_cvt_pk_bf16_f32 v111, v112, v113
	v_cvt_pk_bf16_f32 v112, v106, v107
	v_cvt_pk_bf16_f32 v113, v108, v109
	v_lshl_add_u64 v[106:107], s[90:91], 0, v[194:195]
	global_store_dwordx4 v[106:107], v[110:113], off
	v_lshlrev_b32_e32 v108, 16, v112
	v_and_b32_e32 v109, 0xffff0000, v112
	v_lshlrev_b32_e32 v106, 16, v113
	v_and_b32_e32 v107, 0xffff0000, v113
	v_lshlrev_b32_e32 v112, 16, v110
	v_and_b32_e32 v113, 0xffff0000, v110
	v_lshlrev_b32_e32 v110, 16, v111
	v_and_b32_e32 v111, 0xffff0000, v111
	s_mov_b64 s[4:5], 0x48000
	s_waitcnt vmcnt(2)
	v_pk_add_f32 v[110:111], v[188:189], v[110:111]
	s_waitcnt vmcnt(1)
	v_pk_add_f32 v[106:107], v[192:193], v[106:107]
	v_pk_add_f32 v[112:113], v[186:187], v[112:113]
	v_pk_add_f32 v[108:109], v[190:191], v[108:109]
	v_pk_mul_f32 v[188:189], v[198:199], v[110:111]
	v_pk_mul_f32 v[186:187], v[200:201], v[112:113]
	v_pk_mul_f32 v[190:191], v[202:203], v[106:107]
	v_pk_mul_f32 v[192:193], v[204:205], v[108:109]
	v_cvt_pk_bf16_f32 v186, v186, v187
	v_cvt_pk_bf16_f32 v187, v188, v189
	s_nop 0
	v_cvt_pk_bf16_f32 v188, v192, v193
	v_cvt_pk_bf16_f32 v189, v190, v191
	v_lshl_add_u64 v[190:191], s[96:97], 0, v[194:195]
	global_store_dwordx4 v[190:191], v[186:189], off
	s_nop 1
	v_lshl_add_u64 v[188:189], v[184:185], 0, s[4:5]
	v_lshl_add_u64 v[212:213], v[188:189], 0, v[148:149]
	v_lshl_add_u64 v[186:187], v[212:213], 2, s[44:45]
	global_load_dwordx4 v[190:193], v[186:187], off nt
	global_load_dwordx4 v[194:197], v[186:187], off offset:16 nt
	v_lshlrev_b64 v[212:213], 1, v[212:213]
	v_cvt_pk_bf16_f32 v94, v94, v95
	v_cvt_pk_bf16_f32 v95, v96, v97
	v_cvt_pk_bf16_f32 v96, v90, v91
	v_cvt_pk_bf16_f32 v97, v92, v93
	v_lshl_add_u64 v[90:91], s[90:91], 0, v[212:213]
	global_store_dwordx4 v[90:91], v[94:97], off
	v_lshlrev_b32_e32 v92, 16, v96
	v_and_b32_e32 v93, 0xffff0000, v96
	v_lshlrev_b32_e32 v90, 16, v97
	v_and_b32_e32 v91, 0xffff0000, v97
	v_lshlrev_b32_e32 v96, 16, v94
	v_and_b32_e32 v97, 0xffff0000, v94
	v_lshlrev_b32_e32 v94, 16, v95
	v_and_b32_e32 v95, 0xffff0000, v95
	s_mov_b64 s[4:5], 0x50000
	s_waitcnt vmcnt(2)
	v_pk_add_f32 v[94:95], v[192:193], v[94:95]
	s_waitcnt vmcnt(1)
	v_pk_add_f32 v[90:91], v[196:197], v[90:91]
	v_pk_add_f32 v[96:97], v[190:191], v[96:97]
	v_pk_add_f32 v[92:93], v[194:195], v[92:93]
	v_pk_mul_f32 v[192:193], v[198:199], v[94:95]
	v_pk_mul_f32 v[190:191], v[200:201], v[96:97]
	v_pk_mul_f32 v[194:195], v[202:203], v[90:91]
	v_pk_mul_f32 v[196:197], v[204:205], v[92:93]
	v_cvt_pk_bf16_f32 v190, v190, v191
	v_cvt_pk_bf16_f32 v191, v192, v193
	s_nop 0
	v_cvt_pk_bf16_f32 v192, v196, v197
	v_cvt_pk_bf16_f32 v193, v194, v195
	v_lshl_add_u64 v[194:195], s[96:97], 0, v[212:213]
	global_store_dwordx4 v[194:195], v[190:193], off
	s_nop 1
	v_lshl_add_u64 v[192:193], v[184:185], 0, s[4:5]
	v_lshl_add_u64 v[220:221], v[192:193], 0, v[148:149]
	v_lshl_add_u64 v[190:191], v[220:221], 2, s[44:45]
	global_load_dwordx4 v[194:197], v[190:191], off nt
	global_load_dwordx4 v[212:215], v[190:191], off offset:16 nt
	v_lshlrev_b64 v[220:221], 1, v[220:221]
	v_cvt_pk_bf16_f32 v86, v86, v87
	v_cvt_pk_bf16_f32 v87, v88, v89
	v_cvt_pk_bf16_f32 v88, v82, v83
	v_cvt_pk_bf16_f32 v89, v84, v85
	v_lshl_add_u64 v[82:83], s[90:91], 0, v[220:221]
	global_store_dwordx4 v[82:83], v[86:89], off
	v_lshlrev_b32_e32 v84, 16, v88
	v_and_b32_e32 v85, 0xffff0000, v88
	v_lshlrev_b32_e32 v82, 16, v89
	v_and_b32_e32 v83, 0xffff0000, v89
	v_lshlrev_b32_e32 v88, 16, v86
	v_and_b32_e32 v89, 0xffff0000, v86
	v_lshlrev_b32_e32 v86, 16, v87
	v_and_b32_e32 v87, 0xffff0000, v87
	s_mov_b64 s[4:5], 0x58000
	s_waitcnt vmcnt(2)
; __device__ __forceinline__ unsigned cvt_pk_bf16(float lo, float hi) { unsigned r; asm volatile("v_cvt_pk_bf16_f32 %0, %1, %2" : "=v"(r) : "v"(lo), "v"(hi)); return r; }
;     __device__ __forceinline__ void operator()(const f32x4 (&acc)[2][2][4][2], const Unit& u, int wr, int wc, int fr, int fq) const {
;     ...
;                 for (int m = 0; m < 4; ++m) { const size_t off = (size_t)(row0 + ai * HALF + m * 16) * 2048 + col0 + bj * HALF;
;                     f32x4 x0 = __builtin_nontemporal_load((const f32x4*)(base + off)), x1 = __builtin_nontemporal_load((const f32x4*)(base + off + 4));
;                     if constexpr (HAS_DIN) { const u32x4 dw = __builtin_nontemporal_load((const u32x4*)(dbuf + off));
;                         x0 += (f32x4){__builtin_bit_cast(float, dw.x << 16), __builtin_bit_cast(float, dw.x & 0xffff0000u), __builtin_bit_cast(float, dw.y << 16), __builtin_bit_cast(float, dw.y & 0xffff0000u)};
;                         x1 += (f32x4){__builtin_bit_cast(float, dw.z << 16), __builtin_bit_cast(float, dw.z & 0xffff0000u), __builtin_bit_cast(float, dw.w << 16), __builtin_bit_cast(float, dw.w & 0xffff0000u)}; }
;                     f32x4 o0, o1;
;                     if constexpr (OUT_DELTA) { const f32x4 d0 = g0 * acc[ai][bj][m][0], d1 = g1 * acc[ai][bj][m][1];
;                         u32x4 w; w.x = cvt_pk_bf16(d0[0], d0[1]); w.y = cvt_pk_bf16(d0[2], d0[3]); w.z = cvt_pk_bf16(d1[0], d1[1]); w.w = cvt_pk_bf16(d1[2], d1[3]);
;                         *(u32x4*)(dbuf + off) = w;
;                         o0 = x0 + (f32x4){__builtin_bit_cast(float, w.x << 16), __builtin_bit_cast(float, w.x & 0xffff0000u), __builtin_bit_cast(float, w.y << 16), __builtin_bit_cast(float, w.y & 0xffff0000u)};
;                         o1 = x1 + (f32x4){__builtin_bit_cast(float, w.z << 16), __builtin_bit_cast(float, w.z & 0xffff0000u), __builtin_bit_cast(float, w.w << 16), __builtin_bit_cast(float, w.w & 0xffff0000u)}; }
;                     else { o0 = x0 + g0 * acc[ai][bj][m][0]; o1 = x1 + g1 * acc[ai][bj][m][1]; *(f32x4*)(out + off) = o0; *(f32x4*)(out + off + 4) = o1; }
;                     if (Hn) { const f32x4 h0 = o0 * G0, h1 = o1 * G1;
;                         u32x4 w; w.x = cvt_pk_bf16(h0[0], h0[1]); w.y = cvt_pk_bf16(h0[2], h0[3]); w.z = cvt_pk_bf16(h1[0], h1[1]); w.w = cvt_pk_bf16(h1[2], h1[3]);
;                         *(u32x4*)(Hn + off) = w;
	v_pk_add_f32 v[86:87], v[196:197], v[86:87]
	s_waitcnt vmcnt(1)
	v_pk_add_f32 v[82:83], v[214:215], v[82:83]
	v_pk_add_f32 v[88:89], v[194:195], v[88:89]
	v_pk_add_f32 v[84:85], v[212:213], v[84:85]
	v_pk_mul_f32 v[196:197], v[198:199], v[86:87]
	v_pk_mul_f32 v[194:195], v[200:201], v[88:89]
	v_pk_mul_f32 v[212:213], v[202:203], v[82:83]
	v_pk_mul_f32 v[214:215], v[204:205], v[84:85]
	v_cvt_pk_bf16_f32 v194, v194, v195
	v_cvt_pk_bf16_f32 v195, v196, v197
	s_nop 0
	v_cvt_pk_bf16_f32 v196, v214, v215
	v_cvt_pk_bf16_f32 v197, v212, v213
	v_lshl_add_u64 v[212:213], s[96:97], 0, v[220:221]
	global_store_dwordx4 v[212:213], v[194:197], off
	s_nop 1
	v_lshl_add_u64 v[196:197], v[184:185], 0, s[4:5]
	v_lshl_add_u64 v[224:225], v[196:197], 0, v[148:149]
	v_lshl_add_u64 v[194:195], v[224:225], 2, s[44:45]
	global_load_dwordx4 v[212:215], v[194:195], off nt
	global_load_dwordx4 v[220:223], v[194:195], off offset:16 nt
	v_lshlrev_b64 v[102:103], 1, v[224:225]
	v_cvt_pk_bf16_f32 v78, v78, v79
	v_cvt_pk_bf16_f32 v79, v80, v81
	v_cvt_pk_bf16_f32 v80, v74, v75
	v_cvt_pk_bf16_f32 v81, v76, v77
	v_lshl_add_u64 v[74:75], s[90:91], 0, v[102:103]
	global_store_dwordx4 v[74:75], v[78:81], off
	v_lshlrev_b32_e32 v76, 16, v80
	v_and_b32_e32 v77, 0xffff0000, v80
	v_lshlrev_b32_e32 v74, 16, v81
	v_and_b32_e32 v75, 0xffff0000, v81
	v_lshlrev_b32_e32 v80, 16, v78
	v_and_b32_e32 v81, 0xffff0000, v78
	v_lshlrev_b32_e32 v78, 16, v79
	v_and_b32_e32 v79, 0xffff0000, v79
	v_lshl_add_u64 v[102:103], s[96:97], 0, v[102:103]
	v_or_b32_e32 v148, 0x80, v148
	s_waitcnt vmcnt(2)
	v_pk_add_f32 v[78:79], v[214:215], v[78:79]
	v_pk_add_f32 v[80:81], v[212:213], v[80:81]
	s_waitcnt vmcnt(1)
	v_pk_add_f32 v[74:75], v[222:223], v[74:75]
	v_pk_add_f32 v[76:77], v[220:221], v[76:77]
	v_pk_mul_f32 v[100:101], v[198:199], v[78:79]
	v_pk_mul_f32 v[98:99], v[200:201], v[80:81]
	v_pk_mul_f32 v[104:105], v[202:203], v[74:75]
	v_pk_mul_f32 v[198:199], v[204:205], v[76:77]
	v_cvt_pk_bf16_f32 v98, v98, v99
	v_cvt_pk_bf16_f32 v99, v100, v101
	s_nop 0
	v_cvt_pk_bf16_f32 v100, v198, v199
	v_cvt_pk_bf16_f32 v101, v104, v105
	global_store_dwordx4 v[102:103], v[98:101], off
	global_load_dwordx4 v[100:103], v[178:179], off offset:512 nt
	global_load_dwordx4 v[198:201], v[178:179], off offset:528 nt
	v_lshl_add_u64 v[98:99], v[184:185], 0, v[148:149]
	v_pk_mul_f32 v[104:105], v[68:69], v[28:29]
	v_pk_mul_f32 v[68:69], v[66:67], v[26:27]
	v_cvt_pk_bf16_f32 v66, v70, v71
	v_cvt_pk_bf16_f32 v67, v72, v73
	s_nop 0
	v_cvt_pk_bf16_f32 v68, v68, v69
	v_cvt_pk_bf16_f32 v69, v104, v105
	v_lshlrev_b64 v[104:105], 1, v[98:99]
	v_lshl_add_u64 v[70:71], s[90:91], 0, v[104:105]
	global_store_dwordx4 v[70:71], v[66:69], off
	v_lshlrev_b32_e32 v72, 16, v68
	v_and_b32_e32 v73, 0xffff0000, v68
	v_lshlrev_b32_e32 v68, 16, v69
	v_and_b32_e32 v69, 0xffff0000, v69
	s_waitcnt vmcnt(1)
	v_pk_add_f32 v[70:71], v[200:201], v[68:69]
	v_lshlrev_b32_e32 v68, 16, v66
	v_and_b32_e32 v69, 0xffff0000, v66
	v_lshlrev_b32_e32 v66, 16, v67
	v_and_b32_e32 v67, 0xffff0000, v67
	v_pk_add_f32 v[98:99], v[102:103], v[66:67]
	v_pk_add_f32 v[100:101], v[100:101], v[68:69]
	v_pk_add_f32 v[72:73], v[198:199], v[72:73]
	v_pk_mul_f32 v[68:69], v[150:151], v[98:99]
	v_pk_mul_f32 v[66:67], v[152:153], v[100:101]
	v_pk_mul_f32 v[102:103], v[154:155], v[70:71]
	v_pk_mul_f32 v[178:179], v[156:157], v[72:73]
	v_cvt_pk_bf16_f32 v66, v66, v67
	v_cvt_pk_bf16_f32 v67, v68, v69
	s_nop 0
	v_cvt_pk_bf16_f32 v68, v178, v179
	v_cvt_pk_bf16_f32 v69, v102, v103
	v_lshl_add_u64 v[102:103], s[96:97], 0, v[104:105]
	global_store_dwordx4 v[102:103], v[66:69], off
	s_nop 1
	v_mul_f32_e32 v66, v101, v101
	v_mul_f32_e32 v67, v99, v99
	v_fmac_f32_e32 v66, v100, v100
	v_fmac_f32_e32 v67, v98, v98
	v_add_f32_e32 v66, v66, v67
	v_mul_f32_e32 v67, v73, v73
	v_mul_f32_e32 v68, v71, v71
	v_fmac_f32_e32 v67, v72, v72
	v_fmac_f32_e32 v68, v70, v70
	v_add_f32_e32 v67, v67, v68
	global_load_dwordx4 v[68:71], v[138:139], off offset:512 nt
	global_load_dwordx4 v[98:101], v[138:139], off offset:528 nt
	v_lshl_add_u64 v[72:73], v[140:141], 0, v[148:149]
	v_lshlrev_b64 v[72:73], 1, v[72:73]
	v_cvt_pk_bf16_f32 v62, v62, v63
	v_cvt_pk_bf16_f32 v63, v64, v65
	v_cvt_pk_bf16_f32 v64, v58, v59
	v_cvt_pk_bf16_f32 v65, v60, v61
	v_lshl_add_u64 v[58:59], s[90:91], 0, v[72:73]
	global_store_dwordx4 v[58:59], v[62:65], off
	v_lshlrev_b32_e32 v60, 16, v64
	v_and_b32_e32 v61, 0xffff0000, v64
	v_lshlrev_b32_e32 v58, 16, v65
	v_and_b32_e32 v59, 0xffff0000, v65
	v_lshlrev_b32_e32 v64, 16, v62
	v_and_b32_e32 v65, 0xffff0000, v62
	v_lshlrev_b32_e32 v62, 16, v63
	v_and_b32_e32 v63, 0xffff0000, v63
	v_lshl_add_u64 v[72:73], s[96:97], 0, v[72:73]
	v_add_f32_e32 v66, v66, v67
	v_add_f32_e32 v66, v211, v66
	s_waitcnt vmcnt(2)
	v_pk_add_f32 v[62:63], v[70:71], v[62:63]
	v_pk_add_f32 v[64:65], v[68:69], v[64:65]
	s_waitcnt vmcnt(1)
	v_pk_add_f32 v[58:59], v[100:101], v[58:59]
	v_pk_add_f32 v[60:61], v[98:99], v[60:61]
	v_pk_mul_f32 v[70:71], v[150:151], v[62:63]
	v_pk_mul_f32 v[68:69], v[152:153], v[64:65]
	v_pk_mul_f32 v[98:99], v[154:155], v[58:59]
	v_pk_mul_f32 v[100:101], v[156:157], v[60:61]
	v_cvt_pk_bf16_f32 v68, v68, v69
	v_cvt_pk_bf16_f32 v69, v70, v71
	s_nop 0
	v_cvt_pk_bf16_f32 v70, v100, v101
	v_cvt_pk_bf16_f32 v71, v98, v99
	global_store_dwordx4 v[72:73], v[68:71], off
	global_load_dwordx4 v[68:71], v[142:143], off offset:512 nt
	s_nop 0
	global_load_dwordx4 v[98:101], v[142:143], off offset:528 nt
	v_lshl_add_u64 v[72:73], v[144:145], 0, v[148:149]
	v_lshlrev_b64 v[72:73], 1, v[72:73]
	v_cvt_pk_bf16_f32 v54, v54, v55
	v_cvt_pk_bf16_f32 v55, v56, v57
	v_cvt_pk_bf16_f32 v56, v50, v51
	v_cvt_pk_bf16_f32 v57, v52, v53
	v_lshl_add_u64 v[50:51], s[90:91], 0, v[72:73]
	global_store_dwordx4 v[50:51], v[54:57], off
	v_lshlrev_b32_e32 v52, 16, v56
	v_and_b32_e32 v53, 0xffff0000, v56
	v_lshlrev_b32_e32 v50, 16, v57
	v_and_b32_e32 v51, 0xffff0000, v57
	v_lshlrev_b32_e32 v56, 16, v54
	v_and_b32_e32 v57, 0xffff0000, v54
	v_lshlrev_b32_e32 v54, 16, v55
	v_and_b32_e32 v55, 0xffff0000, v55
	v_lshl_add_u64 v[72:73], s[96:97], 0, v[72:73]
	s_waitcnt vmcnt(2)
; __device__ __forceinline__ unsigned cvt_pk_bf16(float lo, float hi) { unsigned r; asm volatile("v_cvt_pk_bf16_f32 %0, %1, %2" : "=v"(r) : "v"(lo), "v"(hi)); return r; }
;     __device__ __forceinline__ void operator()(const f32x4 (&acc)[2][2][4][2], const Unit& u, int wr, int wc, int fr, int fq) const {
;     ...
;                 for (int m = 0; m < 4; ++m) { const size_t off = (size_t)(row0 + ai * HALF + m * 16) * 2048 + col0 + bj * HALF;
;                     f32x4 x0 = __builtin_nontemporal_load((const f32x4*)(base + off)), x1 = __builtin_nontemporal_load((const f32x4*)(base + off + 4));
;                     if constexpr (HAS_DIN) { const u32x4 dw = __builtin_nontemporal_load((const u32x4*)(dbuf + off));
;                         x0 += (f32x4){__builtin_bit_cast(float, dw.x << 16), __builtin_bit_cast(float, dw.x & 0xffff0000u), __builtin_bit_cast(float, dw.y << 16), __builtin_bit_cast(float, dw.y & 0xffff0000u)};
;                         x1 += (f32x4){__builtin_bit_cast(float, dw.z << 16), __builtin_bit_cast(float, dw.z & 0xffff0000u), __builtin_bit_cast(float, dw.w << 16), __builtin_bit_cast(float, dw.w & 0xffff0000u)}; }
;                     f32x4 o0, o1;
;                     if constexpr (OUT_DELTA) { const f32x4 d0 = g0 * acc[ai][bj][m][0], d1 = g1 * acc[ai][bj][m][1];
;                         u32x4 w; w.x = cvt_pk_bf16(d0[0], d0[1]); w.y = cvt_pk_bf16(d0[2], d0[3]); w.z = cvt_pk_bf16(d1[0], d1[1]); w.w = cvt_pk_bf16(d1[2], d1[3]);
;                         *(u32x4*)(dbuf + off) = w;
;                         o0 = x0 + (f32x4){__builtin_bit_cast(float, w.x << 16), __builtin_bit_cast(float, w.x & 0xffff0000u), __builtin_bit_cast(float, w.y << 16), __builtin_bit_cast(float, w.y & 0xffff0000u)};
;                         o1 = x1 + (f32x4){__builtin_bit_cast(float, w.z << 16), __builtin_bit_cast(float, w.z & 0xffff0000u), __builtin_bit_cast(float, w.w << 16), __builtin_bit_cast(float, w.w & 0xffff0000u)}; }
;                     else { o0 = x0 + g0 * acc[ai][bj][m][0]; o1 = x1 + g1 * acc[ai][bj][m][1]; *(f32x4*)(out + off) = o0; *(f32x4*)(out + off + 4) = o1; }
;                     if (Hn) { const f32x4 h0 = o0 * G0, h1 = o1 * G1;
;                         u32x4 w; w.x = cvt_pk_bf16(h0[0], h0[1]); w.y = cvt_pk_bf16(h0[2], h0[3]); w.z = cvt_pk_bf16(h1[0], h1[1]); w.w = cvt_pk_bf16(h1[2], h1[3]);
;                         *(u32x4*)(Hn + off) = w;
	v_pk_add_f32 v[54:55], v[70:71], v[54:55]
	v_pk_add_f32 v[56:57], v[68:69], v[56:57]
	s_waitcnt vmcnt(1)
	v_pk_add_f32 v[50:51], v[100:101], v[50:51]
	v_pk_add_f32 v[52:53], v[98:99], v[52:53]
	v_pk_mul_f32 v[70:71], v[150:151], v[54:55]
	v_pk_mul_f32 v[68:69], v[152:153], v[56:57]
	v_pk_mul_f32 v[98:99], v[154:155], v[50:51]
	v_pk_mul_f32 v[100:101], v[156:157], v[52:53]
	v_cvt_pk_bf16_f32 v68, v68, v69
	v_cvt_pk_bf16_f32 v69, v70, v71
	s_nop 0
	v_cvt_pk_bf16_f32 v70, v100, v101
	v_cvt_pk_bf16_f32 v71, v98, v99
	global_store_dwordx4 v[72:73], v[68:71], off
	global_load_dwordx4 v[68:71], v[158:159], off offset:512 nt
	s_nop 0
	global_load_dwordx4 v[98:101], v[158:159], off offset:528 nt
	v_lshl_add_u64 v[72:73], v[160:161], 0, v[148:149]
	v_lshlrev_b64 v[72:73], 1, v[72:73]
	v_cvt_pk_bf16_f32 v46, v46, v47
	v_cvt_pk_bf16_f32 v47, v48, v49
	v_cvt_pk_bf16_f32 v48, v42, v43
	v_cvt_pk_bf16_f32 v49, v44, v45
	v_lshl_add_u64 v[42:43], s[90:91], 0, v[72:73]
	global_store_dwordx4 v[42:43], v[46:49], off
	v_lshlrev_b32_e32 v44, 16, v48
	v_and_b32_e32 v45, 0xffff0000, v48
	v_lshlrev_b32_e32 v42, 16, v49
	v_and_b32_e32 v43, 0xffff0000, v49
	v_lshlrev_b32_e32 v48, 16, v46
	v_and_b32_e32 v49, 0xffff0000, v46
	v_lshlrev_b32_e32 v46, 16, v47
	v_and_b32_e32 v47, 0xffff0000, v47
	v_lshl_add_u64 v[72:73], s[96:97], 0, v[72:73]
	s_waitcnt vmcnt(2)
	v_pk_add_f32 v[46:47], v[70:71], v[46:47]
	v_pk_add_f32 v[48:49], v[68:69], v[48:49]
	s_waitcnt vmcnt(1)
	v_pk_add_f32 v[42:43], v[100:101], v[42:43]
	v_pk_add_f32 v[44:45], v[98:99], v[44:45]
	v_pk_mul_f32 v[70:71], v[150:151], v[46:47]
	v_pk_mul_f32 v[68:69], v[152:153], v[48:49]
	v_pk_mul_f32 v[98:99], v[154:155], v[42:43]
	v_pk_mul_f32 v[100:101], v[156:157], v[44:45]
	v_cvt_pk_bf16_f32 v68, v68, v69
	v_cvt_pk_bf16_f32 v69, v70, v71
	s_nop 0
	v_cvt_pk_bf16_f32 v70, v100, v101
	v_cvt_pk_bf16_f32 v71, v98, v99
	global_store_dwordx4 v[72:73], v[68:71], off
	global_load_dwordx4 v[68:71], v[180:181], off offset:512 nt
	s_nop 0
	global_load_dwordx4 v[98:101], v[180:181], off offset:528 nt
	v_lshl_add_u64 v[72:73], v[182:183], 0, v[148:149]
	v_lshlrev_b64 v[72:73], 1, v[72:73]
	v_cvt_pk_bf16_f32 v38, v38, v39
	v_cvt_pk_bf16_f32 v39, v40, v41
	v_cvt_pk_bf16_f32 v40, v34, v35
	v_cvt_pk_bf16_f32 v41, v36, v37
	v_lshl_add_u64 v[34:35], s[90:91], 0, v[72:73]
	global_store_dwordx4 v[34:35], v[38:41], off
	v_lshlrev_b32_e32 v36, 16, v40
	v_and_b32_e32 v37, 0xffff0000, v40
	v_lshlrev_b32_e32 v34, 16, v41
	v_and_b32_e32 v35, 0xffff0000, v41
	v_lshlrev_b32_e32 v40, 16, v38
	v_and_b32_e32 v41, 0xffff0000, v38
	v_lshlrev_b32_e32 v38, 16, v39
	v_and_b32_e32 v39, 0xffff0000, v39
	v_lshl_add_u64 v[72:73], s[96:97], 0, v[72:73]
	s_waitcnt vmcnt(2)
	v_pk_add_f32 v[38:39], v[70:71], v[38:39]
	v_pk_add_f32 v[40:41], v[68:69], v[40:41]
	s_waitcnt vmcnt(1)
	v_pk_add_f32 v[34:35], v[100:101], v[34:35]
	v_pk_add_f32 v[36:37], v[98:99], v[36:37]
	v_pk_mul_f32 v[70:71], v[150:151], v[38:39]
	v_pk_mul_f32 v[68:69], v[152:153], v[40:41]
	v_pk_mul_f32 v[98:99], v[154:155], v[34:35]
	v_pk_mul_f32 v[100:101], v[156:157], v[36:37]
	v_cvt_pk_bf16_f32 v68, v68, v69
	v_cvt_pk_bf16_f32 v69, v70, v71
	s_nop 0
	v_cvt_pk_bf16_f32 v70, v100, v101
	v_cvt_pk_bf16_f32 v71, v98, v99
	global_store_dwordx4 v[72:73], v[68:71], off
	global_load_dwordx4 v[68:71], v[186:187], off offset:512 nt
	s_nop 0
	global_load_dwordx4 v[98:101], v[186:187], off offset:528 nt
	v_lshl_add_u64 v[72:73], v[188:189], 0, v[148:149]
	v_lshlrev_b64 v[72:73], 1, v[72:73]
	v_cvt_pk_bf16_f32 v22, v22, v23
	v_cvt_pk_bf16_f32 v23, v24, v25
	v_cvt_pk_bf16_f32 v24, v18, v19
	v_cvt_pk_bf16_f32 v25, v20, v21
	v_lshl_add_u64 v[18:19], s[90:91], 0, v[72:73]
	global_store_dwordx4 v[18:19], v[22:25], off
	v_lshlrev_b32_e32 v20, 16, v24
	v_and_b32_e32 v21, 0xffff0000, v24
	v_lshlrev_b32_e32 v18, 16, v25
	v_and_b32_e32 v19, 0xffff0000, v25
	v_lshlrev_b32_e32 v24, 16, v22
	v_and_b32_e32 v25, 0xffff0000, v22
	v_lshlrev_b32_e32 v22, 16, v23
	v_and_b32_e32 v23, 0xffff0000, v23
	v_lshl_add_u64 v[72:73], s[96:97], 0, v[72:73]
	s_waitcnt vmcnt(2)
	v_pk_add_f32 v[22:23], v[70:71], v[22:23]
	v_pk_add_f32 v[24:25], v[68:69], v[24:25]
	s_waitcnt vmcnt(1)
; __device__ __forceinline__ unsigned cvt_pk_bf16(float lo, float hi) { unsigned r; asm volatile("v_cvt_pk_bf16_f32 %0, %1, %2" : "=v"(r) : "v"(lo), "v"(hi)); return r; }
;     __device__ __forceinline__ void operator()(const f32x4 (&acc)[2][2][4][2], const Unit& u, int wr, int wc, int fr, int fq) const {
;     ...
;                 for (int m = 0; m < 4; ++m) { const size_t off = (size_t)(row0 + ai * HALF + m * 16) * 2048 + col0 + bj * HALF;
;                     f32x4 x0 = __builtin_nontemporal_load((const f32x4*)(base + off)), x1 = __builtin_nontemporal_load((const f32x4*)(base + off + 4));
;                     if constexpr (HAS_DIN) { const u32x4 dw = __builtin_nontemporal_load((const u32x4*)(dbuf + off));
;                         x0 += (f32x4){__builtin_bit_cast(float, dw.x << 16), __builtin_bit_cast(float, dw.x & 0xffff0000u), __builtin_bit_cast(float, dw.y << 16), __builtin_bit_cast(float, dw.y & 0xffff0000u)};
;                         x1 += (f32x4){__builtin_bit_cast(float, dw.z << 16), __builtin_bit_cast(float, dw.z & 0xffff0000u), __builtin_bit_cast(float, dw.w << 16), __builtin_bit_cast(float, dw.w & 0xffff0000u)}; }
;                     f32x4 o0, o1;
;                     if constexpr (OUT_DELTA) { const f32x4 d0 = g0 * acc[ai][bj][m][0], d1 = g1 * acc[ai][bj][m][1];
;                         u32x4 w; w.x = cvt_pk_bf16(d0[0], d0[1]); w.y = cvt_pk_bf16(d0[2], d0[3]); w.z = cvt_pk_bf16(d1[0], d1[1]); w.w = cvt_pk_bf16(d1[2], d1[3]);
;                         *(u32x4*)(dbuf + off) = w;
;                         o0 = x0 + (f32x4){__builtin_bit_cast(float, w.x << 16), __builtin_bit_cast(float, w.x & 0xffff0000u), __builtin_bit_cast(float, w.y << 16), __builtin_bit_cast(float, w.y & 0xffff0000u)};
;                         o1 = x1 + (f32x4){__builtin_bit_cast(float, w.z << 16), __builtin_bit_cast(float, w.z & 0xffff0000u), __builtin_bit_cast(float, w.w << 16), __builtin_bit_cast(float, w.w & 0xffff0000u)}; }
;                     else { o0 = x0 + g0 * acc[ai][bj][m][0]; o1 = x1 + g1 * acc[ai][bj][m][1]; *(f32x4*)(out + off) = o0; *(f32x4*)(out + off + 4) = o1; }
;                     if (Hn) { const f32x4 h0 = o0 * G0, h1 = o1 * G1;
;                         u32x4 w; w.x = cvt_pk_bf16(h0[0], h0[1]); w.y = cvt_pk_bf16(h0[2], h0[3]); w.z = cvt_pk_bf16(h1[0], h1[1]); w.w = cvt_pk_bf16(h1[2], h1[3]);
;                         *(u32x4*)(Hn + off) = w;
	v_pk_add_f32 v[18:19], v[100:101], v[18:19]
	v_pk_add_f32 v[20:21], v[98:99], v[20:21]
	v_pk_mul_f32 v[70:71], v[150:151], v[22:23]
	v_pk_mul_f32 v[68:69], v[152:153], v[24:25]
	v_pk_mul_f32 v[98:99], v[154:155], v[18:19]
	v_pk_mul_f32 v[100:101], v[156:157], v[20:21]
	v_cvt_pk_bf16_f32 v68, v68, v69
	v_cvt_pk_bf16_f32 v69, v70, v71
	s_nop 0
	v_cvt_pk_bf16_f32 v70, v100, v101
	v_cvt_pk_bf16_f32 v71, v98, v99
	global_store_dwordx4 v[72:73], v[68:71], off
	global_load_dwordx4 v[68:71], v[190:191], off offset:512 nt
	s_nop 0
	global_load_dwordx4 v[98:101], v[190:191], off offset:528 nt
	v_lshl_add_u64 v[72:73], v[192:193], 0, v[148:149]
	v_lshlrev_b64 v[72:73], 1, v[72:73]
	v_cvt_pk_bf16_f32 v14, v14, v15
	v_cvt_pk_bf16_f32 v15, v16, v17
	v_cvt_pk_bf16_f32 v16, v10, v11
	v_cvt_pk_bf16_f32 v17, v12, v13
	v_lshl_add_u64 v[10:11], s[90:91], 0, v[72:73]
	global_store_dwordx4 v[10:11], v[14:17], off
	v_lshlrev_b32_e32 v12, 16, v16
	v_and_b32_e32 v13, 0xffff0000, v16
	v_lshlrev_b32_e32 v10, 16, v17
	v_and_b32_e32 v11, 0xffff0000, v17
	v_lshlrev_b32_e32 v16, 16, v14
	v_and_b32_e32 v17, 0xffff0000, v14
	v_lshlrev_b32_e32 v14, 16, v15
	v_and_b32_e32 v15, 0xffff0000, v15
	v_lshl_add_u64 v[72:73], s[96:97], 0, v[72:73]
	s_waitcnt vmcnt(2)
	v_pk_add_f32 v[14:15], v[70:71], v[14:15]
	v_pk_add_f32 v[16:17], v[68:69], v[16:17]
	s_waitcnt vmcnt(1)
	v_pk_add_f32 v[10:11], v[100:101], v[10:11]
	v_pk_add_f32 v[12:13], v[98:99], v[12:13]
	v_pk_mul_f32 v[70:71], v[150:151], v[14:15]
	v_pk_mul_f32 v[68:69], v[152:153], v[16:17]
	v_pk_mul_f32 v[98:99], v[154:155], v[10:11]
	v_pk_mul_f32 v[100:101], v[156:157], v[12:13]
	v_cvt_pk_bf16_f32 v68, v68, v69
	v_cvt_pk_bf16_f32 v69, v70, v71
	s_nop 0
	v_cvt_pk_bf16_f32 v70, v100, v101
	v_cvt_pk_bf16_f32 v71, v98, v99
	global_store_dwordx4 v[72:73], v[68:71], off
	global_load_dwordx4 v[68:71], v[194:195], off offset:512 nt
	s_nop 0
	global_load_dwordx4 v[98:101], v[194:195], off offset:528 nt
	v_lshl_add_u64 v[72:73], v[196:197], 0, v[148:149]
	v_lshlrev_b64 v[30:31], 1, v[72:73]
	v_cvt_pk_bf16_f32 v6, v6, v7
	v_cvt_pk_bf16_f32 v7, v8, v9
	v_cvt_pk_bf16_f32 v8, v2, v3
	v_cvt_pk_bf16_f32 v9, v4, v5
	v_lshl_add_u64 v[2:3], s[90:91], 0, v[30:31]
	global_store_dwordx4 v[2:3], v[6:9], off
	v_lshlrev_b32_e32 v4, 16, v8
	v_and_b32_e32 v5, 0xffff0000, v8
	v_lshlrev_b32_e32 v2, 16, v9
	v_and_b32_e32 v3, 0xffff0000, v9
	v_lshlrev_b32_e32 v8, 16, v6
	v_and_b32_e32 v9, 0xffff0000, v6
	v_lshlrev_b32_e32 v6, 16, v7
	v_and_b32_e32 v7, 0xffff0000, v7
	v_lshl_add_u64 v[30:31], s[96:97], 0, v[30:31]
	s_waitcnt vmcnt(2)
	v_pk_add_f32 v[8:9], v[68:69], v[8:9]
	v_pk_add_f32 v[6:7], v[70:71], v[6:7]
	v_pk_mul_f32 v[26:27], v[152:153], v[8:9]
	s_waitcnt vmcnt(1)
	v_pk_add_f32 v[2:3], v[100:101], v[2:3]
	v_pk_add_f32 v[4:5], v[98:99], v[4:5]
	v_pk_mul_f32 v[28:29], v[150:151], v[6:7]
	v_cvt_pk_bf16_f32 v26, v26, v27
	v_pk_mul_f32 v[32:33], v[154:155], v[2:3]
	v_cvt_pk_bf16_f32 v27, v28, v29
	v_pk_mul_f32 v[68:69], v[156:157], v[4:5]
	s_nop 0
	v_cvt_pk_bf16_f32 v28, v68, v69
	v_cvt_pk_bf16_f32 v29, v32, v33
	global_store_dwordx4 v[30:31], v[26:29], off
	s_nop 1
	v_and_b32_e32 v27, 64, v218
	v_xor_b32_e32 v26, 16, v218
	v_add_u32_e32 v27, 64, v27
	v_cmp_lt_i32_e32 vcc, v26, v27
	s_nop 1
	v_cndmask_b32_e32 v26, v218, v26, vcc
	v_lshlrev_b32_e32 v28, 2, v26
	v_xor_b32_e32 v26, 32, v218
	v_cmp_lt_i32_e32 vcc, v26, v27
	s_nop 1
	v_cndmask_b32_e32 v26, v218, v26, vcc
	v_lshlrev_b32_e32 v29, 2, v26
	ds_bpermute_b32 v26, v28, v66
	s_waitcnt lgkmcnt(0)
	v_add_f32_e32 v30, v66, v26
	ds_bpermute_b32 v31, v29, v30
	v_lshl_add_u64 v[26:27], v[146:147], 3, s[42:43]
	s_and_saveexec_b64 s[4:5], s[0:1]
	s_mov_b32 s8, 0x2f800000
	s_mov_b32 s9, 0xcf800000
	s_cbranch_execz .LBB0_558
	s_waitcnt lgkmcnt(0)
	v_add_f32_e32 v30, v30, v31
	v_mul_f32_e32 v30, 0x47800000, v30
	v_rndne_f32_e32 v30, v30
	v_mul_f32_e64 v31, |v30|, s8
	v_floor_f32_e32 v31, v31
	v_fma_f32 v32, v31, s9, |v30|
	v_cvt_u32_f32_e32 v32, v32
	v_cvt_u32_f32_e32 v31, v31
	v_ashrrev_i32_e32 v33, 31, v30
	v_xor_b32_e32 v30, v32, v33
	v_xor_b32_e32 v31, v31, v33
	v_sub_co_u32_e32 v30, vcc, v30, v33
	s_nop 1
	v_subb_co_u32_e32 v31, vcc, v31, v33, vcc
	global_atomic_add_x2 v[26:27], v[30:31], off

; #define PG8_STAGE(bufoff, gbase, voff) do { const char* gb_ = (const char*)(gbase); asm volatile("" : "+s"(gb_)); _Pragma("unroll") for (int _i = 0; _i < 2; ++_i) { unsigned vo_ = (voff)[_i]; asm volatile("" : "+v"(vo_));        \
;         __builtin_amdgcn_global_load_lds((const unsigned*)(gb_ + vo_), (PG8_LAS unsigned*)(lds + (bufoff) + ldsw + _i * 8192), 16, 0, 0); } } while (0)
; #define PG8_LDA(dst, b, h) do { _Pragma("unroll") for (int m = 0; m < 4; ++m) _Pragma("unroll") for (int k = 0; k < 2; ++k) dst[m][k] = *(const PG8_LAS bf16x8*)(lds + PG8_SA(b, h) + aoff + m * 2048 + k * 1024); } while (0)
; #define PG8_LDB(dst, b, h) do { _Pragma("unroll") for (int n = 0; n < 2; ++n) _Pragma("unroll") for (int k = 0; k < 2; ++k) dst[n][k] = *(const PG8_LAS bf16x8*)(lds + PG8_SB(b, h) + boff + n * 2048 + k * 1024); } while (0)
; #define PG8_MMA(ai, bj, At, Bt) do { __builtin_amdgcn_s_setprio(1); _Pragma("unroll") for (int m = 0; m < 4; ++m) _Pragma("unroll") for (int n = 0; n < 2; ++n) _Pragma("unroll") for (int k = 0; k < 2; ++k) \
;         acc[ai][bj][m][n] = __builtin_amdgcn_mfma_f32_16x16x32_bf16(Bt[n][k], At[m][k], acc[ai][bj][m][n], 0, 0, 0); __builtin_amdgcn_s_setprio(0); } while (0)
; #define PG8_WAIT_V(n) asm volatile("s_waitcnt vmcnt(" #n ")" ::: "memory")
; template <class Epi, class Sched, bool ALIGN_EPI = false, bool SP2 = false>
; __device__ __forceinline__ void gemm_phase(PG8_LAS unsigned char* lds, const Gemm g, const Sched& S, const Epi& E) {
;     ...
;             const bool last = (t == nt - 2);
;             const char* a1 = cA + (size_t)(t + 1) * kstep;
;             const char* a2 = last ? nA : cA + (size_t)(t + 2) * kstep; const char* b2 = last ? nB : cB + (size_t)(t + 2) * kstep;
;             const char* a3 = a2 + kstep; const char* b3 = b2 + kstep;
;             if (last && has_next) S.a_ready(nxt);
;             if constexpr (SP2) {
;             PG8_LDB(B0, 0, 0); PG8_LDB(B1, 0, 1); PG8_SCHED; PG8_LDA(At, 0, 0); PG8_STAGE(PG8_SA(1, 1), a1 + hstep, voffA);
;             PG8_WAIT_V(8); PG8_WAIT_L(0); PG8_BAR; PG8_MMA(0, 0, At, B0); PG8_MMA(0, 1, At, B1); PG8_BAR; PG8_SCHED;
;             PG8_LDA(At, 0, 1); PG8_STAGE(PG8_SB(0, 0), b2, voffB); PG8_STAGE(PG8_SB(0, 1), b2 + hstep, voffB); PG8_STAGE(PG8_SA(0, 0), a2, voffA);
;             PG8_WAIT_V(8); PG8_WAIT_L(0); PG8_BAR; PG8_MMA(1, 0, At, B0); PG8_MMA(1, 1, At, B1); PG8_BAR; PG8_SCHED;
.LBB0_634:
	s_add_u32 s16, s14, 0x100
	s_addc_u32 s17, s15, 0
	s_cmp_eq_u32 s53, 28
	s_cselect_b32 s22, s49, s16
	s_cselect_b32 s23, s7, s17
	s_cselect_b32 s20, s50, s51
	s_cselect_b32 s21, s5, s52
	s_add_u32 s18, s22, 0x80
	s_addc_u32 s19, s23, 0
	s_add_i32 s54, 0, 0x10000
	s_add_i32 s55, 0, 0x14000
	v_add_u32_e32 v94, s54, v186
	v_add_u32_e32 v158, s55, v186
	ds_read_b128 v[82:85], v94
	ds_read_b128 v[86:89], v94 offset:1024
	ds_read_b128 v[90:93], v94 offset:2048
	ds_read_b128 v[94:97], v94 offset:3072
	ds_read_b128 v[146:149], v158
	ds_read_b128 v[150:153], v158 offset:1024
	ds_read_b128 v[154:157], v158 offset:2048
	ds_read_b128 v[158:161], v158 offset:3072
	s_add_u32 s14, s14, 0x80080
	s_addc_u32 s15, s15, 0
	v_mov_b32_e32 v182, v1
	ds_read_b128 v[178:181], v188
	ds_read_b128 v[190:193], v188 offset:1024
	ds_read_b128 v[194:197], v188 offset:2048
	ds_read_b128 v[198:201], v188 offset:3072
	ds_read_b128 v[202:205], v188 offset:4096
	ds_read_b128 v[206:209], v188 offset:5120
	ds_read_b128 v[210:213], v188 offset:6144
	ds_read_b128 v[220:223], v188 offset:7168
	s_add_i32 m0, s27, 0xc000
	s_nop 0
	global_load_lds_dwordx4 v182, s[14:15]
	v_mov_b32_e32 v182, v164
	s_add_i32 m0, s27, 0xe000
	s_nop 0
	global_load_lds_dwordx4 v182, s[14:15]
	s_waitcnt vmcnt(8)
	s_waitcnt lgkmcnt(0)
	s_barrier
	s_setprio 1
	s_waitcnt lgkmcnt(0)
	v_mfma_f32_16x16x32_bf16 v[142:145], v[82:85], v[178:181], v[142:145]
	v_mfma_f32_16x16x32_bf16 v[142:145], v[86:89], v[190:193], v[142:145]
	v_mfma_f32_16x16x32_bf16 v[126:129], v[82:85], v[194:197], v[126:129]
	v_mfma_f32_16x16x32_bf16 v[126:129], v[86:89], v[198:201], v[126:129]
	v_mfma_f32_16x16x32_bf16 v[110:113], v[82:85], v[202:205], v[110:113]
	v_mfma_f32_16x16x32_bf16 v[110:113], v[86:89], v[206:209], v[110:113]
	v_mfma_f32_16x16x32_bf16 v[78:81], v[82:85], v[210:213], v[78:81]
	v_mfma_f32_16x16x32_bf16 v[78:81], v[86:89], v[220:223], v[78:81]
	v_mfma_f32_16x16x32_bf16 v[138:141], v[90:93], v[178:181], v[138:141]
	v_mfma_f32_16x16x32_bf16 v[138:141], v[94:97], v[190:193], v[138:141]
	v_mfma_f32_16x16x32_bf16 v[122:125], v[90:93], v[194:197], v[122:125]
	v_mfma_f32_16x16x32_bf16 v[122:125], v[94:97], v[198:201], v[122:125]
	v_mfma_f32_16x16x32_bf16 v[106:109], v[90:93], v[202:205], v[106:109]
	v_mfma_f32_16x16x32_bf16 v[106:109], v[94:97], v[206:209], v[106:109]
	v_mfma_f32_16x16x32_bf16 v[74:77], v[90:93], v[210:213], v[74:77]
	v_mfma_f32_16x16x32_bf16 v[74:77], v[94:97], v[220:223], v[74:77]
	s_setprio 0
	s_setprio 1
	v_mfma_f32_16x16x32_bf16 v[134:137], v[146:149], v[178:181], v[134:137]
	v_mfma_f32_16x16x32_bf16 v[134:137], v[150:153], v[190:193], v[134:137]
	v_mfma_f32_16x16x32_bf16 v[118:121], v[146:149], v[194:197], v[118:121]
	v_mfma_f32_16x16x32_bf16 v[118:121], v[150:153], v[198:201], v[118:121]
	v_mfma_f32_16x16x32_bf16 v[102:105], v[146:149], v[202:205], v[102:105]
	v_mfma_f32_16x16x32_bf16 v[102:105], v[150:153], v[206:209], v[102:105]
	v_mfma_f32_16x16x32_bf16 v[70:73], v[146:149], v[210:213], v[70:73]
	v_mfma_f32_16x16x32_bf16 v[70:73], v[150:153], v[220:223], v[70:73]
	v_mfma_f32_16x16x32_bf16 v[130:133], v[154:157], v[178:181], v[130:133]
	v_mfma_f32_16x16x32_bf16 v[130:133], v[158:161], v[190:193], v[130:133]
	v_mfma_f32_16x16x32_bf16 v[114:117], v[154:157], v[194:197], v[114:117]
	v_mfma_f32_16x16x32_bf16 v[114:117], v[158:161], v[198:201], v[114:117]
	v_mfma_f32_16x16x32_bf16 v[98:101], v[154:157], v[202:205], v[98:101]
	v_mfma_f32_16x16x32_bf16 v[98:101], v[158:161], v[206:209], v[98:101]
	v_mfma_f32_16x16x32_bf16 v[66:69], v[154:157], v[210:213], v[66:69]
	v_mfma_f32_16x16x32_bf16 v[66:69], v[158:161], v[220:223], v[66:69]
	s_setprio 0
	s_barrier
	s_mov_b64 s[14:15], s[20:21]
	v_mov_b32_e32 v182, v162
	s_add_i32 s54, s54, s26
	ds_read_b128 v[178:181], v188 offset:16384
	ds_read_b128 v[190:193], v188 offset:17408
	ds_read_b128 v[194:197], v188 offset:18432
	ds_read_b128 v[198:201], v188 offset:19456
	ds_read_b128 v[202:205], v188 offset:20480
	ds_read_b128 v[206:209], v188 offset:21504
	ds_read_b128 v[210:213], v188 offset:22528
	ds_read_b128 v[220:223], v188 offset:23552
	s_mov_b32 m0, s54
	s_nop 0
	global_load_lds_dwordx4 v182, s[14:15]
	v_mov_b32_e32 v182, v184
	s_add_i32 m0, s54, 0x2000
	s_nop 0
	global_load_lds_dwordx4 v182, s[14:15]
	s_add_u32 s14, s20, 0x80000
	s_addc_u32 s15, s21, 0
	v_mov_b32_e32 v182, v162
	s_add_i32 s54, s55, s26
	s_mov_b32 m0, s54
	s_nop 0
	global_load_lds_dwordx4 v182, s[14:15]
	v_mov_b32_e32 v182, v184
	s_add_i32 m0, s54, 0x2000
	s_nop 0
	global_load_lds_dwordx4 v182, s[14:15]
	s_mov_b64 s[14:15], s[22:23]
	v_mov_b32_e32 v182, v1
	s_mov_b32 m0, s27
	s_nop 0
	global_load_lds_dwordx4 v182, s[14:15]
	v_mov_b32_e32 v182, v164
	s_mov_b32 m0, s28
	s_nop 0
	global_load_lds_dwordx4 v182, s[14:15]
	s_waitcnt vmcnt(8)
	s_waitcnt lgkmcnt(0)
	s_barrier
; #define PG8_STAGE(bufoff, gbase, voff) do { const char* gb_ = (const char*)(gbase); asm volatile("" : "+s"(gb_)); _Pragma("unroll") for (int _i = 0; _i < 2; ++_i) { unsigned vo_ = (voff)[_i]; asm volatile("" : "+v"(vo_));        \
;         __builtin_amdgcn_global_load_lds((const unsigned*)(gb_ + vo_), (PG8_LAS unsigned*)(lds + (bufoff) + ldsw + _i * 8192), 16, 0, 0); } } while (0)
; #define PG8_LDA(dst, b, h) do { _Pragma("unroll") for (int m = 0; m < 4; ++m) _Pragma("unroll") for (int k = 0; k < 2; ++k) dst[m][k] = *(const PG8_LAS bf16x8*)(lds + PG8_SA(b, h) + aoff + m * 2048 + k * 1024); } while (0)
; #define PG8_LDB(dst, b, h) do { _Pragma("unroll") for (int n = 0; n < 2; ++n) _Pragma("unroll") for (int k = 0; k < 2; ++k) dst[n][k] = *(const PG8_LAS bf16x8*)(lds + PG8_SB(b, h) + boff + n * 2048 + k * 1024); } while (0)
; #define PG8_MMA(ai, bj, At, Bt) do { __builtin_amdgcn_s_setprio(1); _Pragma("unroll") for (int m = 0; m < 4; ++m) _Pragma("unroll") for (int n = 0; n < 2; ++n) _Pragma("unroll") for (int k = 0; k < 2; ++k) \
;         acc[ai][bj][m][n] = __builtin_amdgcn_mfma_f32_16x16x32_bf16(Bt[n][k], At[m][k], acc[ai][bj][m][n], 0, 0, 0); __builtin_amdgcn_s_setprio(0); } while (0)
; #define PG8_WAIT_V(n) asm volatile("s_waitcnt vmcnt(" #n ")" ::: "memory")
; #define PG8_WAIT_L(n) asm volatile("s_waitcnt lgkmcnt(" #n ")" ::: "memory")
; #define PG8_BAR __builtin_amdgcn_s_barrier()
; #define PG8_SCHED __builtin_amdgcn_sched_barrier(0)
; template <class Epi, class Sched, bool ALIGN_EPI = false, bool SP2 = false>
; __device__ __forceinline__ void gemm_phase(PG8_LAS unsigned char* lds, const Gemm g, const Sched& S, const Epi& E) {
;     ...
;             PG8_WAIT_V(8); PG8_WAIT_L(0); PG8_BAR; PG8_MMA(1, 0, At, B0); PG8_MMA(1, 1, At, B1); PG8_BAR; PG8_SCHED;
;             PG8_LDB(B0, 1, 0); PG8_LDB(B1, 1, 1); PG8_SCHED; PG8_LDA(At, 1, 0); PG8_STAGE(PG8_SA(0, 1), a2 + hstep, voffA);
;             PG8_WAIT_V(8); PG8_WAIT_L(0); PG8_BAR; PG8_MMA(0, 0, At, B0); PG8_MMA(0, 1, At, B1); PG8_BAR; PG8_SCHED;
;             PG8_LDA(At, 1, 1); PG8_STAGE(PG8_SB(1, 0), b3, voffB); PG8_STAGE(PG8_SB(1, 1), b3 + hstep, voffB); PG8_STAGE(PG8_SA(1, 0), a3, voffA);
	s_setprio 1
	s_waitcnt lgkmcnt(0)
	v_mfma_f32_16x16x32_bf16 v[62:65], v[82:85], v[178:181], v[62:65]
	v_mfma_f32_16x16x32_bf16 v[62:65], v[86:89], v[190:193], v[62:65]
	v_mfma_f32_16x16x32_bf16 v[46:49], v[82:85], v[194:197], v[46:49]
	v_mfma_f32_16x16x32_bf16 v[46:49], v[86:89], v[198:201], v[46:49]
	v_mfma_f32_16x16x32_bf16 v[30:33], v[82:85], v[202:205], v[30:33]
	v_mfma_f32_16x16x32_bf16 v[30:33], v[86:89], v[206:209], v[30:33]
	v_mfma_f32_16x16x32_bf16 v[14:17], v[82:85], v[210:213], v[14:17]
	v_mfma_f32_16x16x32_bf16 v[14:17], v[86:89], v[220:223], v[14:17]
	v_mfma_f32_16x16x32_bf16 v[58:61], v[90:93], v[178:181], v[58:61]
	v_mfma_f32_16x16x32_bf16 v[58:61], v[94:97], v[190:193], v[58:61]
	v_mfma_f32_16x16x32_bf16 v[42:45], v[90:93], v[194:197], v[42:45]
	v_mfma_f32_16x16x32_bf16 v[42:45], v[94:97], v[198:201], v[42:45]
	v_mfma_f32_16x16x32_bf16 v[26:29], v[90:93], v[202:205], v[26:29]
	v_mfma_f32_16x16x32_bf16 v[26:29], v[94:97], v[206:209], v[26:29]
	v_mfma_f32_16x16x32_bf16 v[10:13], v[90:93], v[210:213], v[10:13]
	v_mfma_f32_16x16x32_bf16 v[10:13], v[94:97], v[220:223], v[10:13]
	s_setprio 0
	s_setprio 1
	v_mfma_f32_16x16x32_bf16 v[54:57], v[146:149], v[178:181], v[54:57]
	v_mfma_f32_16x16x32_bf16 v[54:57], v[150:153], v[190:193], v[54:57]
	v_mfma_f32_16x16x32_bf16 v[38:41], v[146:149], v[194:197], v[38:41]
	v_mfma_f32_16x16x32_bf16 v[38:41], v[150:153], v[198:201], v[38:41]
	v_mfma_f32_16x16x32_bf16 v[22:25], v[146:149], v[202:205], v[22:25]
	v_mfma_f32_16x16x32_bf16 v[22:25], v[150:153], v[206:209], v[22:25]
	v_mfma_f32_16x16x32_bf16 v[6:9], v[146:149], v[210:213], v[6:9]
	v_mfma_f32_16x16x32_bf16 v[6:9], v[150:153], v[220:223], v[6:9]
	v_mfma_f32_16x16x32_bf16 v[50:53], v[154:157], v[178:181], v[50:53]
	v_mfma_f32_16x16x32_bf16 v[50:53], v[158:161], v[190:193], v[50:53]
	v_mfma_f32_16x16x32_bf16 v[34:37], v[154:157], v[194:197], v[34:37]
	v_mfma_f32_16x16x32_bf16 v[34:37], v[158:161], v[198:201], v[34:37]
	v_mfma_f32_16x16x32_bf16 v[18:21], v[154:157], v[202:205], v[18:21]
	v_mfma_f32_16x16x32_bf16 v[18:21], v[158:161], v[206:209], v[18:21]
	v_mfma_f32_16x16x32_bf16 v[2:5], v[154:157], v[210:213], v[2:5]
	v_mfma_f32_16x16x32_bf16 v[2:5], v[158:161], v[220:223], v[2:5]
	s_setprio 0
	s_barrier
	s_add_i32 s54, 0, 0x18000
	s_add_i32 s55, 0, 0x1c000
	v_add_u32_e32 v94, s54, v186
	v_add_u32_e32 v158, s55, v186
	ds_read_b128 v[82:85], v94
	ds_read_b128 v[86:89], v94 offset:1024
	ds_read_b128 v[90:93], v94 offset:2048
	ds_read_b128 v[94:97], v94 offset:3072
	ds_read_b128 v[146:149], v158
	ds_read_b128 v[150:153], v158 offset:1024
	ds_read_b128 v[154:157], v158 offset:2048
	ds_read_b128 v[158:161], v158 offset:3072
	s_add_u32 s14, s22, 0x80000
	s_addc_u32 s15, s23, 0
	v_mov_b32_e32 v182, v1
	s_mov_b32 m0, s29
	ds_read_b128 v[178:181], v188 offset:32768
	ds_read_b128 v[190:193], v188 offset:33792
	ds_read_b128 v[194:197], v188 offset:34816
	ds_read_b128 v[198:201], v188 offset:35840
	ds_read_b128 v[202:205], v188 offset:36864
	ds_read_b128 v[206:209], v188 offset:37888
	ds_read_b128 v[210:213], v188 offset:38912
	ds_read_b128 v[220:223], v188 offset:39936
	s_nop 0
	global_load_lds_dwordx4 v182, s[14:15]
	v_mov_b32_e32 v182, v164
	s_mov_b32 m0, s33
	s_nop 0
	global_load_lds_dwordx4 v182, s[14:15]
	s_waitcnt vmcnt(8)
	s_waitcnt lgkmcnt(0)
	s_barrier
	s_setprio 1
	s_waitcnt lgkmcnt(0)
	v_mfma_f32_16x16x32_bf16 v[142:145], v[82:85], v[178:181], v[142:145]
	v_mfma_f32_16x16x32_bf16 v[142:145], v[86:89], v[190:193], v[142:145]
	v_mfma_f32_16x16x32_bf16 v[126:129], v[82:85], v[194:197], v[126:129]
	v_mfma_f32_16x16x32_bf16 v[126:129], v[86:89], v[198:201], v[126:129]
	v_mfma_f32_16x16x32_bf16 v[110:113], v[82:85], v[202:205], v[110:113]
	v_mfma_f32_16x16x32_bf16 v[110:113], v[86:89], v[206:209], v[110:113]
	v_mfma_f32_16x16x32_bf16 v[78:81], v[82:85], v[210:213], v[78:81]
	v_mfma_f32_16x16x32_bf16 v[78:81], v[86:89], v[220:223], v[78:81]
	v_mfma_f32_16x16x32_bf16 v[138:141], v[90:93], v[178:181], v[138:141]
	v_mfma_f32_16x16x32_bf16 v[138:141], v[94:97], v[190:193], v[138:141]
	v_mfma_f32_16x16x32_bf16 v[122:125], v[90:93], v[194:197], v[122:125]
	v_mfma_f32_16x16x32_bf16 v[122:125], v[94:97], v[198:201], v[122:125]
	v_mfma_f32_16x16x32_bf16 v[106:109], v[90:93], v[202:205], v[106:109]
	v_mfma_f32_16x16x32_bf16 v[106:109], v[94:97], v[206:209], v[106:109]
	v_mfma_f32_16x16x32_bf16 v[74:77], v[90:93], v[210:213], v[74:77]
	v_mfma_f32_16x16x32_bf16 v[74:77], v[94:97], v[220:223], v[74:77]
	s_setprio 0
	s_setprio 1
	v_mfma_f32_16x16x32_bf16 v[134:137], v[146:149], v[178:181], v[134:137]
	v_mfma_f32_16x16x32_bf16 v[134:137], v[150:153], v[190:193], v[134:137]
	v_mfma_f32_16x16x32_bf16 v[118:121], v[146:149], v[194:197], v[118:121]
	v_mfma_f32_16x16x32_bf16 v[118:121], v[150:153], v[198:201], v[118:121]
	v_mfma_f32_16x16x32_bf16 v[102:105], v[146:149], v[202:205], v[102:105]
	v_mfma_f32_16x16x32_bf16 v[102:105], v[150:153], v[206:209], v[102:105]
	v_mfma_f32_16x16x32_bf16 v[70:73], v[146:149], v[210:213], v[70:73]
	v_mfma_f32_16x16x32_bf16 v[70:73], v[150:153], v[220:223], v[70:73]
	v_mfma_f32_16x16x32_bf16 v[130:133], v[154:157], v[178:181], v[130:133]
	v_mfma_f32_16x16x32_bf16 v[130:133], v[158:161], v[190:193], v[130:133]
	v_mfma_f32_16x16x32_bf16 v[114:117], v[154:157], v[194:197], v[114:117]
	v_mfma_f32_16x16x32_bf16 v[114:117], v[158:161], v[198:201], v[114:117]
	v_mfma_f32_16x16x32_bf16 v[98:101], v[154:157], v[202:205], v[98:101]
	v_mfma_f32_16x16x32_bf16 v[98:101], v[158:161], v[206:209], v[98:101]
	v_mfma_f32_16x16x32_bf16 v[66:69], v[154:157], v[210:213], v[66:69]
	v_mfma_f32_16x16x32_bf16 v[66:69], v[158:161], v[220:223], v[66:69]
	s_setprio 0
	s_barrier
; #define PG8_STAGE(bufoff, gbase, voff) do { const char* gb_ = (const char*)(gbase); asm volatile("" : "+s"(gb_)); _Pragma("unroll") for (int _i = 0; _i < 2; ++_i) { unsigned vo_ = (voff)[_i]; asm volatile("" : "+v"(vo_));        \
;         __builtin_amdgcn_global_load_lds((const unsigned*)(gb_ + vo_), (PG8_LAS unsigned*)(lds + (bufoff) + ldsw + _i * 8192), 16, 0, 0); } } while (0)
; #define PG8_LDA(dst, b, h) do { _Pragma("unroll") for (int m = 0; m < 4; ++m) _Pragma("unroll") for (int k = 0; k < 2; ++k) dst[m][k] = *(const PG8_LAS bf16x8*)(lds + PG8_SA(b, h) + aoff + m * 2048 + k * 1024); } while (0)
; #define PG8_MMA(ai, bj, At, Bt) do { __builtin_amdgcn_s_setprio(1); _Pragma("unroll") for (int m = 0; m < 4; ++m) _Pragma("unroll") for (int n = 0; n < 2; ++n) _Pragma("unroll") for (int k = 0; k < 2; ++k) \
;         acc[ai][bj][m][n] = __builtin_amdgcn_mfma_f32_16x16x32_bf16(Bt[n][k], At[m][k], acc[ai][bj][m][n], 0, 0, 0); __builtin_amdgcn_s_setprio(0); } while (0)
; #define PG8_WAIT_V(n) asm volatile("s_waitcnt vmcnt(" #n ")" ::: "memory")
; #define PG8_WAIT_L(n) asm volatile("s_waitcnt lgkmcnt(" #n ")" ::: "memory")
; #define PG8_BAR __builtin_amdgcn_s_barrier()
; #define PG8_SCHED __builtin_amdgcn_sched_barrier(0)
; template <class Epi, class Sched, bool ALIGN_EPI = false, bool SP2 = false>
; __device__ __forceinline__ void gemm_phase(PG8_LAS unsigned char* lds, const Gemm g, const Sched& S, const Epi& E) {
;     ...
;             PG8_LDA(At, 1, 1); PG8_STAGE(PG8_SB(1, 0), b3, voffB); PG8_STAGE(PG8_SB(1, 1), b3 + hstep, voffB); PG8_STAGE(PG8_SA(1, 0), a3, voffA);
;             PG8_WAIT_V(8); PG8_WAIT_L(0); PG8_BAR; PG8_MMA(1, 0, At, B0); PG8_MMA(1, 1, At, B1); PG8_BAR; PG8_SCHED;
;     ...
;         if constexpr (ALIGN_EPI) { if (wr == 0) PG8_BAR; }
	s_add_u32 s14, s20, 0x80
	s_addc_u32 s15, s21, 0
	v_mov_b32_e32 v182, v162
	s_add_i32 s22, s54, s26
	ds_read_b128 v[178:181], v188 offset:49152
	ds_read_b128 v[190:193], v188 offset:50176
	ds_read_b128 v[194:197], v188 offset:51200
	ds_read_b128 v[198:201], v188 offset:52224
	ds_read_b128 v[202:205], v188 offset:53248
	ds_read_b128 v[206:209], v188 offset:54272
	ds_read_b128 v[210:213], v188 offset:55296
	ds_read_b128 v[220:223], v188 offset:56320
	s_mov_b32 m0, s22
	s_nop 0
	global_load_lds_dwordx4 v182, s[14:15]
	v_mov_b32_e32 v182, v184
	s_add_i32 m0, s22, 0x2000
	s_nop 0
	global_load_lds_dwordx4 v182, s[14:15]
	s_add_u32 s14, s20, 0x80080
	s_addc_u32 s15, s21, 0
	v_mov_b32_e32 v182, v162
	s_add_i32 s20, s55, s26
	s_mov_b32 m0, s20
	s_nop 0
	global_load_lds_dwordx4 v182, s[14:15]
	v_mov_b32_e32 v182, v184
	s_add_i32 m0, s20, 0x2000
	s_nop 0
	global_load_lds_dwordx4 v182, s[14:15]
	v_mov_b32_e32 v182, v1
	s_mov_b32 m0, s38
	s_nop 0
	global_load_lds_dwordx4 v182, s[18:19]
	v_mov_b32_e32 v182, v164
	s_mov_b32 m0, s39
	s_nop 0
	global_load_lds_dwordx4 v182, s[18:19]
	s_waitcnt vmcnt(8)
	s_waitcnt lgkmcnt(0)
	s_barrier
	s_setprio 1
	s_waitcnt lgkmcnt(0)
	v_mfma_f32_16x16x32_bf16 v[62:65], v[82:85], v[178:181], v[62:65]
	v_mfma_f32_16x16x32_bf16 v[62:65], v[86:89], v[190:193], v[62:65]
	v_mfma_f32_16x16x32_bf16 v[46:49], v[82:85], v[194:197], v[46:49]
	v_mfma_f32_16x16x32_bf16 v[46:49], v[86:89], v[198:201], v[46:49]
	v_mfma_f32_16x16x32_bf16 v[30:33], v[82:85], v[202:205], v[30:33]
	v_mfma_f32_16x16x32_bf16 v[30:33], v[86:89], v[206:209], v[30:33]
	v_mfma_f32_16x16x32_bf16 v[14:17], v[82:85], v[210:213], v[14:17]
	v_mfma_f32_16x16x32_bf16 v[14:17], v[86:89], v[220:223], v[14:17]
	v_mfma_f32_16x16x32_bf16 v[58:61], v[90:93], v[178:181], v[58:61]
	v_mfma_f32_16x16x32_bf16 v[58:61], v[94:97], v[190:193], v[58:61]
	v_mfma_f32_16x16x32_bf16 v[42:45], v[90:93], v[194:197], v[42:45]
	v_mfma_f32_16x16x32_bf16 v[42:45], v[94:97], v[198:201], v[42:45]
	v_mfma_f32_16x16x32_bf16 v[26:29], v[90:93], v[202:205], v[26:29]
	v_mfma_f32_16x16x32_bf16 v[26:29], v[94:97], v[206:209], v[26:29]
	v_mfma_f32_16x16x32_bf16 v[10:13], v[90:93], v[210:213], v[10:13]
	v_mfma_f32_16x16x32_bf16 v[10:13], v[94:97], v[220:223], v[10:13]
	s_setprio 0
	s_setprio 1
	v_mfma_f32_16x16x32_bf16 v[54:57], v[146:149], v[178:181], v[54:57]
	v_mfma_f32_16x16x32_bf16 v[54:57], v[150:153], v[190:193], v[54:57]
	v_mfma_f32_16x16x32_bf16 v[38:41], v[146:149], v[194:197], v[38:41]
	v_mfma_f32_16x16x32_bf16 v[38:41], v[150:153], v[198:201], v[38:41]
	v_mfma_f32_16x16x32_bf16 v[22:25], v[146:149], v[202:205], v[22:25]
	v_mfma_f32_16x16x32_bf16 v[22:25], v[150:153], v[206:209], v[22:25]
	v_mfma_f32_16x16x32_bf16 v[6:9], v[146:149], v[210:213], v[6:9]
	v_mfma_f32_16x16x32_bf16 v[6:9], v[150:153], v[220:223], v[6:9]
	v_mfma_f32_16x16x32_bf16 v[50:53], v[154:157], v[178:181], v[50:53]
	v_mfma_f32_16x16x32_bf16 v[50:53], v[158:161], v[190:193], v[50:53]
	v_mfma_f32_16x16x32_bf16 v[34:37], v[154:157], v[194:197], v[34:37]
	v_mfma_f32_16x16x32_bf16 v[34:37], v[158:161], v[198:201], v[34:37]
	v_mfma_f32_16x16x32_bf16 v[18:21], v[154:157], v[202:205], v[18:21]
	v_mfma_f32_16x16x32_bf16 v[18:21], v[158:161], v[206:209], v[18:21]
	v_mfma_f32_16x16x32_bf16 v[2:5], v[154:157], v[210:213], v[2:5]
	v_mfma_f32_16x16x32_bf16 v[2:5], v[158:161], v[220:223], v[2:5]
	s_setprio 0
	s_barrier
	s_add_i32 s53, s53, 2
	s_add_u32 s51, s51, 0x100
	s_addc_u32 s52, s52, 0
	s_cmp_gt_u32 s53, 29
	s_mov_b64 s[14:15], s[16:17]
	s_cbranch_scc0 .LBB0_634
	s_and_b64 vcc, exec, s[2:3]
	s_cbranch_vccz .LBB0_637
	s_barrier

; #define PG8_STAGE(bufoff, gbase, voff) do { const char* gb_ = (const char*)(gbase); asm volatile("" : "+s"(gb_)); _Pragma("unroll") for (int _i = 0; _i < 2; ++_i) { unsigned vo_ = (voff)[_i]; asm volatile("" : "+v"(vo_));        \
;         __builtin_amdgcn_global_load_lds((const unsigned*)(gb_ + vo_), (PG8_LAS unsigned*)(lds + (bufoff) + ldsw + _i * 8192), 16, 0, 0); } } while (0)
; #define PG8_LDA(dst, b, h) do { _Pragma("unroll") for (int m = 0; m < 4; ++m) _Pragma("unroll") for (int k = 0; k < 2; ++k) dst[m][k] = *(const PG8_LAS bf16x8*)(lds + PG8_SA(b, h) + aoff + m * 2048 + k * 1024); } while (0)
; #define PG8_LDB(dst, b, h) do { _Pragma("unroll") for (int n = 0; n < 2; ++n) _Pragma("unroll") for (int k = 0; k < 2; ++k) dst[n][k] = *(const PG8_LAS bf16x8*)(lds + PG8_SB(b, h) + boff + n * 2048 + k * 1024); } while (0)
; #define PG8_MMA(ai, bj, At, Bt) do { __builtin_amdgcn_s_setprio(1); _Pragma("unroll") for (int m = 0; m < 4; ++m) _Pragma("unroll") for (int n = 0; n < 2; ++n) _Pragma("unroll") for (int k = 0; k < 2; ++k) \
;         acc[ai][bj][m][n] = __builtin_amdgcn_mfma_f32_16x16x32_bf16(Bt[n][k], At[m][k], acc[ai][bj][m][n], 0, 0, 0); __builtin_amdgcn_s_setprio(0); } while (0)
; #define PG8_WAIT_V(n) asm volatile("s_waitcnt vmcnt(" #n ")" ::: "memory")
; template <class Epi, class Sched, bool ALIGN_EPI = false, bool SP2 = false>
; __device__ __forceinline__ void gemm_phase(PG8_LAS unsigned char* lds, const Gemm g, const Sched& S, const Epi& E) {
;     ...
;             const bool last = (t == nt - 2);
;             const char* a1 = cA + (size_t)(t + 1) * kstep;
;             const char* a2 = last ? nA : cA + (size_t)(t + 2) * kstep; const char* b2 = last ? nB : cB + (size_t)(t + 2) * kstep;
;             const char* a3 = a2 + kstep; const char* b3 = b2 + kstep;
;             if (last && has_next) S.a_ready(nxt);
;             if constexpr (SP2) {
;             PG8_LDB(B0, 0, 0); PG8_LDB(B1, 0, 1); PG8_SCHED; PG8_LDA(At, 0, 0); PG8_STAGE(PG8_SA(1, 1), a1 + hstep, voffA);
;             PG8_WAIT_V(8); PG8_WAIT_L(0); PG8_BAR; PG8_MMA(0, 0, At, B0); PG8_MMA(0, 1, At, B1); PG8_BAR; PG8_SCHED;
;             PG8_LDA(At, 0, 1); PG8_STAGE(PG8_SB(0, 0), b2, voffB); PG8_STAGE(PG8_SB(0, 1), b2 + hstep, voffB); PG8_STAGE(PG8_SA(0, 0), a2, voffA);
;             PG8_WAIT_V(8); PG8_WAIT_L(0); PG8_BAR; PG8_MMA(1, 0, At, B0); PG8_MMA(1, 1, At, B1); PG8_BAR; PG8_SCHED;
.LBB0_707:
	s_add_u32 s2, s4, 0x100
	s_addc_u32 s3, s5, 0
	s_cmpk_eq_i32 s35, 0x54
	s_cselect_b32 s10, s52, s2
	s_cselect_b32 s11, s53, s3
	s_cselect_b32 s8, s42, s31
	s_cselect_b32 s9, s43, s34
	s_add_u32 s6, s10, 0x80
	s_addc_u32 s7, s11, 0
	s_add_i32 s38, 0, 0x10000
	s_add_i32 s39, 0, 0x14000
	v_add_u32_e32 v102, s38, v192
	v_add_u32_e32 v158, s39, v192
	ds_read_b128 v[34:37], v102
	ds_read_b128 v[38:41], v102 offset:1024
	ds_read_b128 v[98:101], v102 offset:2048
	ds_read_b128 v[102:105], v102 offset:3072
	ds_read_b128 v[146:149], v158
	ds_read_b128 v[150:153], v158 offset:1024
	ds_read_b128 v[154:157], v158 offset:2048
	ds_read_b128 v[158:161], v158 offset:3072
	s_add_u32 s4, s4, 0x160080
	s_addc_u32 s5, s5, 0
	v_mov_b32_e32 v195, v1
	ds_read_b128 v[178:181], v194
	ds_read_b128 v[182:185], v194 offset:1024
	ds_read_b128 v[186:189], v194 offset:2048
	ds_read_b128 v[196:199], v194 offset:3072
	ds_read_b128 v[200:203], v194 offset:4096
	ds_read_b128 v[204:207], v194 offset:5120
	ds_read_b128 v[208:211], v194 offset:6144
	ds_read_b128 v[212:215], v194 offset:7168
	s_add_i32 m0, s16, 0xc000
	s_nop 0
	global_load_lds_dwordx4 v195, s[4:5]
	v_mov_b32_e32 v195, v164
	s_add_i32 m0, s16, 0xe000
	s_nop 0
	global_load_lds_dwordx4 v195, s[4:5]
	s_waitcnt vmcnt(8)
	s_waitcnt lgkmcnt(0)
	s_barrier
	s_setprio 1
	s_waitcnt lgkmcnt(0)
	v_mfma_f32_16x16x32_bf16 v[142:145], v[34:37], v[178:181], v[142:145]
	v_mfma_f32_16x16x32_bf16 v[142:145], v[38:41], v[182:185], v[142:145]
	v_mfma_f32_16x16x32_bf16 v[134:137], v[34:37], v[186:189], v[134:137]
	v_mfma_f32_16x16x32_bf16 v[134:137], v[38:41], v[196:199], v[134:137]
	v_mfma_f32_16x16x32_bf16 v[126:129], v[34:37], v[200:203], v[126:129]
	v_mfma_f32_16x16x32_bf16 v[126:129], v[38:41], v[204:207], v[126:129]
	v_mfma_f32_16x16x32_bf16 v[118:121], v[34:37], v[208:211], v[118:121]
	v_mfma_f32_16x16x32_bf16 v[118:121], v[38:41], v[212:215], v[118:121]
	v_mfma_f32_16x16x32_bf16 v[138:141], v[98:101], v[178:181], v[138:141]
	v_mfma_f32_16x16x32_bf16 v[138:141], v[102:105], v[182:185], v[138:141]
	v_mfma_f32_16x16x32_bf16 v[130:133], v[98:101], v[186:189], v[130:133]
	v_mfma_f32_16x16x32_bf16 v[130:133], v[102:105], v[196:199], v[130:133]
	v_mfma_f32_16x16x32_bf16 v[122:125], v[98:101], v[200:203], v[122:125]
	v_mfma_f32_16x16x32_bf16 v[122:125], v[102:105], v[204:207], v[122:125]
	v_mfma_f32_16x16x32_bf16 v[114:117], v[98:101], v[208:211], v[114:117]
	v_mfma_f32_16x16x32_bf16 v[114:117], v[102:105], v[212:215], v[114:117]
	s_setprio 0
	s_setprio 1
	v_mfma_f32_16x16x32_bf16 v[70:73], v[146:149], v[178:181], v[70:73]
	v_mfma_f32_16x16x32_bf16 v[70:73], v[150:153], v[182:185], v[70:73]
	v_mfma_f32_16x16x32_bf16 v[62:65], v[146:149], v[186:189], v[62:65]
	v_mfma_f32_16x16x32_bf16 v[62:65], v[150:153], v[196:199], v[62:65]
	v_mfma_f32_16x16x32_bf16 v[54:57], v[146:149], v[200:203], v[54:57]
	v_mfma_f32_16x16x32_bf16 v[54:57], v[150:153], v[204:207], v[54:57]
	v_mfma_f32_16x16x32_bf16 v[46:49], v[146:149], v[208:211], v[46:49]
	v_mfma_f32_16x16x32_bf16 v[46:49], v[150:153], v[212:215], v[46:49]
	v_mfma_f32_16x16x32_bf16 v[66:69], v[154:157], v[178:181], v[66:69]
	v_mfma_f32_16x16x32_bf16 v[66:69], v[158:161], v[182:185], v[66:69]
	v_mfma_f32_16x16x32_bf16 v[58:61], v[154:157], v[186:189], v[58:61]
	v_mfma_f32_16x16x32_bf16 v[58:61], v[158:161], v[196:199], v[58:61]
	v_mfma_f32_16x16x32_bf16 v[50:53], v[154:157], v[200:203], v[50:53]
	v_mfma_f32_16x16x32_bf16 v[50:53], v[158:161], v[204:207], v[50:53]
	v_mfma_f32_16x16x32_bf16 v[42:45], v[154:157], v[208:211], v[42:45]
	v_mfma_f32_16x16x32_bf16 v[42:45], v[158:161], v[212:215], v[42:45]
	s_setprio 0
	s_barrier
	s_mov_b64 s[4:5], s[8:9]
	v_mov_b32_e32 v195, v162
	s_add_i32 s38, s38, s15
	ds_read_b128 v[178:181], v194 offset:16384
	ds_read_b128 v[182:185], v194 offset:17408
	ds_read_b128 v[186:189], v194 offset:18432
	ds_read_b128 v[196:199], v194 offset:19456
	ds_read_b128 v[200:203], v194 offset:20480
	ds_read_b128 v[204:207], v194 offset:21504
	ds_read_b128 v[208:211], v194 offset:22528
	ds_read_b128 v[212:215], v194 offset:23552
	s_mov_b32 m0, s38
	s_nop 0
	global_load_lds_dwordx4 v195, s[4:5]
	v_mov_b32_e32 v195, v190
	s_add_i32 m0, s38, 0x2000
	s_nop 0
	global_load_lds_dwordx4 v195, s[4:5]
	s_add_u32 s4, s8, 0x160000
	s_addc_u32 s5, s9, 0
	v_mov_b32_e32 v195, v162
	s_add_i32 s38, s39, s15
	s_mov_b32 m0, s38
	s_nop 0
	global_load_lds_dwordx4 v195, s[4:5]
	v_mov_b32_e32 v195, v190
	s_add_i32 m0, s38, 0x2000
	s_nop 0
	global_load_lds_dwordx4 v195, s[4:5]
	s_mov_b64 s[4:5], s[10:11]
	v_mov_b32_e32 v195, v1
	s_mov_b32 m0, s16
	s_nop 0
	global_load_lds_dwordx4 v195, s[4:5]
	v_mov_b32_e32 v195, v164
	s_mov_b32 m0, s17
	s_nop 0
	global_load_lds_dwordx4 v195, s[4:5]
	s_waitcnt vmcnt(8)
	s_waitcnt lgkmcnt(0)
	s_barrier
; #define PG8_STAGE(bufoff, gbase, voff) do { const char* gb_ = (const char*)(gbase); asm volatile("" : "+s"(gb_)); _Pragma("unroll") for (int _i = 0; _i < 2; ++_i) { unsigned vo_ = (voff)[_i]; asm volatile("" : "+v"(vo_));        \
;         __builtin_amdgcn_global_load_lds((const unsigned*)(gb_ + vo_), (PG8_LAS unsigned*)(lds + (bufoff) + ldsw + _i * 8192), 16, 0, 0); } } while (0)
; #define PG8_LDA(dst, b, h) do { _Pragma("unroll") for (int m = 0; m < 4; ++m) _Pragma("unroll") for (int k = 0; k < 2; ++k) dst[m][k] = *(const PG8_LAS bf16x8*)(lds + PG8_SA(b, h) + aoff + m * 2048 + k * 1024); } while (0)
; #define PG8_LDB(dst, b, h) do { _Pragma("unroll") for (int n = 0; n < 2; ++n) _Pragma("unroll") for (int k = 0; k < 2; ++k) dst[n][k] = *(const PG8_LAS bf16x8*)(lds + PG8_SB(b, h) + boff + n * 2048 + k * 1024); } while (0)
; #define PG8_MMA(ai, bj, At, Bt) do { __builtin_amdgcn_s_setprio(1); _Pragma("unroll") for (int m = 0; m < 4; ++m) _Pragma("unroll") for (int n = 0; n < 2; ++n) _Pragma("unroll") for (int k = 0; k < 2; ++k) \
;         acc[ai][bj][m][n] = __builtin_amdgcn_mfma_f32_16x16x32_bf16(Bt[n][k], At[m][k], acc[ai][bj][m][n], 0, 0, 0); __builtin_amdgcn_s_setprio(0); } while (0)
; #define PG8_WAIT_V(n) asm volatile("s_waitcnt vmcnt(" #n ")" ::: "memory")
; #define PG8_WAIT_L(n) asm volatile("s_waitcnt lgkmcnt(" #n ")" ::: "memory")
; #define PG8_BAR __builtin_amdgcn_s_barrier()
; #define PG8_SCHED __builtin_amdgcn_sched_barrier(0)
; template <class Epi, class Sched, bool ALIGN_EPI = false, bool SP2 = false>
; __device__ __forceinline__ void gemm_phase(PG8_LAS unsigned char* lds, const Gemm g, const Sched& S, const Epi& E) {
;     ...
;             PG8_WAIT_V(8); PG8_WAIT_L(0); PG8_BAR; PG8_MMA(1, 0, At, B0); PG8_MMA(1, 1, At, B1); PG8_BAR; PG8_SCHED;
;             PG8_LDB(B0, 1, 0); PG8_LDB(B1, 1, 1); PG8_SCHED; PG8_LDA(At, 1, 0); PG8_STAGE(PG8_SA(0, 1), a2 + hstep, voffA);
;             PG8_WAIT_V(8); PG8_WAIT_L(0); PG8_BAR; PG8_MMA(0, 0, At, B0); PG8_MMA(0, 1, At, B1); PG8_BAR; PG8_SCHED;
;             PG8_LDA(At, 1, 1); PG8_STAGE(PG8_SB(1, 0), b3, voffB); PG8_STAGE(PG8_SB(1, 1), b3 + hstep, voffB); PG8_STAGE(PG8_SA(1, 0), a3, voffA);
	s_setprio 1
	s_waitcnt lgkmcnt(0)
	v_mfma_f32_16x16x32_bf16 v[110:113], v[34:37], v[178:181], v[110:113]
	v_mfma_f32_16x16x32_bf16 v[106:109], v[98:101], v[178:181], v[106:109]
	v_mfma_f32_16x16x32_bf16 v[94:97], v[34:37], v[186:189], v[94:97]
	v_mfma_f32_16x16x32_bf16 v[90:93], v[98:101], v[186:189], v[90:93]
	v_mfma_f32_16x16x32_bf16 v[86:89], v[34:37], v[200:203], v[86:89]
	v_mfma_f32_16x16x32_bf16 v[82:85], v[98:101], v[200:203], v[82:85]
	v_mfma_f32_16x16x32_bf16 v[34:37], v[34:37], v[208:211], v[78:81]
	v_mfma_f32_16x16x32_bf16 v[110:113], v[38:41], v[182:185], v[110:113]
	v_mfma_f32_16x16x32_bf16 v[106:109], v[102:105], v[182:185], v[106:109]
	v_mfma_f32_16x16x32_bf16 v[94:97], v[38:41], v[196:199], v[94:97]
	v_mfma_f32_16x16x32_bf16 v[90:93], v[102:105], v[196:199], v[90:93]
	v_mfma_f32_16x16x32_bf16 v[86:89], v[38:41], v[204:207], v[86:89]
	v_mfma_f32_16x16x32_bf16 v[82:85], v[102:105], v[204:207], v[82:85]
	v_mfma_f32_16x16x32_bf16 v[34:37], v[38:41], v[212:215], v[34:37]
	v_mfma_f32_16x16x32_bf16 v[38:41], v[98:101], v[208:211], v[74:77]
	v_mfma_f32_16x16x32_bf16 v[38:41], v[102:105], v[212:215], v[38:41]
	s_setprio 0
	s_setprio 1
	v_mfma_f32_16x16x32_bf16 v[30:33], v[146:149], v[178:181], v[30:33]
	v_mfma_f32_16x16x32_bf16 v[30:33], v[150:153], v[182:185], v[30:33]
	v_mfma_f32_16x16x32_bf16 v[22:25], v[146:149], v[186:189], v[22:25]
	v_mfma_f32_16x16x32_bf16 v[22:25], v[150:153], v[196:199], v[22:25]
	v_mfma_f32_16x16x32_bf16 v[14:17], v[146:149], v[200:203], v[14:17]
	v_mfma_f32_16x16x32_bf16 v[14:17], v[150:153], v[204:207], v[14:17]
	v_mfma_f32_16x16x32_bf16 v[6:9], v[146:149], v[208:211], v[6:9]
	v_mfma_f32_16x16x32_bf16 v[6:9], v[150:153], v[212:215], v[6:9]
	v_mfma_f32_16x16x32_bf16 v[26:29], v[154:157], v[178:181], v[26:29]
	v_mfma_f32_16x16x32_bf16 v[26:29], v[158:161], v[182:185], v[26:29]
	v_mfma_f32_16x16x32_bf16 v[18:21], v[154:157], v[186:189], v[18:21]
	v_mfma_f32_16x16x32_bf16 v[18:21], v[158:161], v[196:199], v[18:21]
	v_mfma_f32_16x16x32_bf16 v[10:13], v[154:157], v[200:203], v[10:13]
	v_mfma_f32_16x16x32_bf16 v[10:13], v[158:161], v[204:207], v[10:13]
	v_mfma_f32_16x16x32_bf16 v[2:5], v[154:157], v[208:211], v[2:5]
	v_mfma_f32_16x16x32_bf16 v[2:5], v[158:161], v[212:215], v[2:5]
	s_setprio 0
	s_barrier
	s_add_i32 s38, 0, 0x18000
	s_add_i32 s39, 0, 0x1c000
	v_add_u32_e32 v102, s38, v192
	v_add_u32_e32 v158, s39, v192
	ds_read_b128 v[74:77], v102
	ds_read_b128 v[78:81], v102 offset:1024
	ds_read_b128 v[98:101], v102 offset:2048
	ds_read_b128 v[102:105], v102 offset:3072
	ds_read_b128 v[146:149], v158
	ds_read_b128 v[150:153], v158 offset:1024
	ds_read_b128 v[154:157], v158 offset:2048
	ds_read_b128 v[158:161], v158 offset:3072
	s_add_u32 s4, s10, 0x160000
	s_addc_u32 s5, s11, 0
	v_mov_b32_e32 v195, v1
	s_mov_b32 m0, s18
	ds_read_b128 v[178:181], v194 offset:32768
	ds_read_b128 v[182:185], v194 offset:33792
	ds_read_b128 v[186:189], v194 offset:34816
	ds_read_b128 v[196:199], v194 offset:35840
	ds_read_b128 v[200:203], v194 offset:36864
	ds_read_b128 v[204:207], v194 offset:37888
	ds_read_b128 v[208:211], v194 offset:38912
	ds_read_b128 v[212:215], v194 offset:39936
	s_nop 0
	global_load_lds_dwordx4 v195, s[4:5]
	v_mov_b32_e32 v195, v164
	s_mov_b32 m0, s19
	s_nop 0
	global_load_lds_dwordx4 v195, s[4:5]
	s_waitcnt vmcnt(8)
	s_waitcnt lgkmcnt(0)
	s_barrier
	s_setprio 1
	s_waitcnt lgkmcnt(0)
	v_mfma_f32_16x16x32_bf16 v[142:145], v[74:77], v[178:181], v[142:145]
	v_mfma_f32_16x16x32_bf16 v[142:145], v[78:81], v[182:185], v[142:145]
	v_mfma_f32_16x16x32_bf16 v[134:137], v[74:77], v[186:189], v[134:137]
	v_mfma_f32_16x16x32_bf16 v[134:137], v[78:81], v[196:199], v[134:137]
	v_mfma_f32_16x16x32_bf16 v[126:129], v[74:77], v[200:203], v[126:129]
	v_mfma_f32_16x16x32_bf16 v[126:129], v[78:81], v[204:207], v[126:129]
	v_mfma_f32_16x16x32_bf16 v[118:121], v[74:77], v[208:211], v[118:121]
	v_mfma_f32_16x16x32_bf16 v[118:121], v[78:81], v[212:215], v[118:121]
	v_mfma_f32_16x16x32_bf16 v[138:141], v[98:101], v[178:181], v[138:141]
	v_mfma_f32_16x16x32_bf16 v[138:141], v[102:105], v[182:185], v[138:141]
	v_mfma_f32_16x16x32_bf16 v[130:133], v[98:101], v[186:189], v[130:133]
	v_mfma_f32_16x16x32_bf16 v[130:133], v[102:105], v[196:199], v[130:133]
	v_mfma_f32_16x16x32_bf16 v[122:125], v[98:101], v[200:203], v[122:125]
	v_mfma_f32_16x16x32_bf16 v[122:125], v[102:105], v[204:207], v[122:125]
	v_mfma_f32_16x16x32_bf16 v[114:117], v[98:101], v[208:211], v[114:117]
	v_mfma_f32_16x16x32_bf16 v[114:117], v[102:105], v[212:215], v[114:117]
	s_setprio 0
	s_setprio 1
	v_mfma_f32_16x16x32_bf16 v[70:73], v[146:149], v[178:181], v[70:73]
	v_mfma_f32_16x16x32_bf16 v[70:73], v[150:153], v[182:185], v[70:73]
	v_mfma_f32_16x16x32_bf16 v[62:65], v[146:149], v[186:189], v[62:65]
	v_mfma_f32_16x16x32_bf16 v[62:65], v[150:153], v[196:199], v[62:65]
	v_mfma_f32_16x16x32_bf16 v[54:57], v[146:149], v[200:203], v[54:57]
	v_mfma_f32_16x16x32_bf16 v[54:57], v[150:153], v[204:207], v[54:57]
	v_mfma_f32_16x16x32_bf16 v[46:49], v[146:149], v[208:211], v[46:49]
	v_mfma_f32_16x16x32_bf16 v[46:49], v[150:153], v[212:215], v[46:49]
	v_mfma_f32_16x16x32_bf16 v[66:69], v[154:157], v[178:181], v[66:69]
	v_mfma_f32_16x16x32_bf16 v[66:69], v[158:161], v[182:185], v[66:69]
	v_mfma_f32_16x16x32_bf16 v[58:61], v[154:157], v[186:189], v[58:61]
	v_mfma_f32_16x16x32_bf16 v[58:61], v[158:161], v[196:199], v[58:61]
	v_mfma_f32_16x16x32_bf16 v[50:53], v[154:157], v[200:203], v[50:53]
	v_mfma_f32_16x16x32_bf16 v[50:53], v[158:161], v[204:207], v[50:53]
	v_mfma_f32_16x16x32_bf16 v[42:45], v[154:157], v[208:211], v[42:45]
	v_mfma_f32_16x16x32_bf16 v[42:45], v[158:161], v[212:215], v[42:45]
	s_setprio 0
	s_barrier
; #define PG8_STAGE(bufoff, gbase, voff) do { const char* gb_ = (const char*)(gbase); asm volatile("" : "+s"(gb_)); _Pragma("unroll") for (int _i = 0; _i < 2; ++_i) { unsigned vo_ = (voff)[_i]; asm volatile("" : "+v"(vo_));        \
;         __builtin_amdgcn_global_load_lds((const unsigned*)(gb_ + vo_), (PG8_LAS unsigned*)(lds + (bufoff) + ldsw + _i * 8192), 16, 0, 0); } } while (0)
; #define PG8_LDA(dst, b, h) do { _Pragma("unroll") for (int m = 0; m < 4; ++m) _Pragma("unroll") for (int k = 0; k < 2; ++k) dst[m][k] = *(const PG8_LAS bf16x8*)(lds + PG8_SA(b, h) + aoff + m * 2048 + k * 1024); } while (0)
; #define PG8_WAIT_V(n) asm volatile("s_waitcnt vmcnt(" #n ")" ::: "memory")
; #define PG8_WAIT_L(n) asm volatile("s_waitcnt lgkmcnt(" #n ")" ::: "memory")
; #define PG8_BAR __builtin_amdgcn_s_barrier()
; #define PG8_SCHED __builtin_amdgcn_sched_barrier(0)
;     __device__ __forceinline__ void operator()(const f32x4 (&acc)[2][2][4][2], const Unit& u, int wr, int wc, int fr, int fq) const {
;         const int row0 = u.pm * BM + wr * 64 + fr, col0 = u.pn * BM + wc * 32 + 8 * fq, b = (u.pm * BM) / rows_per_batch;
;         const float* g = gate + (size_t)b * gate_bstride + col0;
;         float ssq[2][4];
; #pragma unroll
;         for (int ai = 0; ai < 2; ++ai)
; #pragma unroll
;             for (int m = 0; m < 4; ++m) ssq[ai][m] = 0.f;
;         f32x4 gv[2][2], Gv[2][2];
; #pragma unroll
;         for (int bj = 0; bj < 2; ++bj) { gv[bj][0] = *(const f32x4*)(g + bj * HALF); gv[bj][1] = *(const f32x4*)(g + bj * HALF + 4); Gv[bj][0] = (f32x4){0.f, 0.f, 0.f, 0.f}; Gv[bj][1] = (f32x4){0.f, 0.f, 0.f, 0.f};
;             if (Hn) { const float* sc = scnext + (size_t)b * gate_bstride + col0 + bj * HALF;
;                 Gv[bj][0] = *(const f32x4*)(gnext + col0 + bj * HALF) * (1.0f + *(const f32x4*)(sc)); Gv[bj][1] = *(const f32x4*)(gnext + col0 + bj * HALF + 4) * (1.0f + *(const f32x4*)(sc + 4)); } }
; template <class Epi, class Sched, bool ALIGN_EPI = false, bool SP2 = false>
; __device__ __forceinline__ void gemm_phase(PG8_LAS unsigned char* lds, const Gemm g, const Sched& S, const Epi& E) {
;     ...
;             PG8_LDA(At, 1, 1); PG8_STAGE(PG8_SB(1, 0), b3, voffB); PG8_STAGE(PG8_SB(1, 1), b3 + hstep, voffB); PG8_STAGE(PG8_SA(1, 0), a3, voffA);
;             PG8_WAIT_V(8); PG8_WAIT_L(0); PG8_BAR; PG8_MMA(1, 0, At, B0); PG8_MMA(1, 1, At, B1); PG8_BAR; PG8_SCHED;
	s_add_u32 s4, s8, 0x80
	s_addc_u32 s5, s9, 0
	v_mov_b32_e32 v195, v162
	s_add_i32 s10, s38, s15
	ds_read_b128 v[178:181], v194 offset:49152
	ds_read_b128 v[182:185], v194 offset:50176
	ds_read_b128 v[186:189], v194 offset:51200
	ds_read_b128 v[196:199], v194 offset:52224
	ds_read_b128 v[200:203], v194 offset:53248
	ds_read_b128 v[204:207], v194 offset:54272
	ds_read_b128 v[208:211], v194 offset:55296
	ds_read_b128 v[212:215], v194 offset:56320
	s_mov_b32 m0, s10
	s_nop 0
	global_load_lds_dwordx4 v195, s[4:5]
	v_mov_b32_e32 v195, v190
	s_add_i32 m0, s10, 0x2000
	s_nop 0
	global_load_lds_dwordx4 v195, s[4:5]
	s_add_u32 s4, s8, 0x160080
	s_addc_u32 s5, s9, 0
	v_mov_b32_e32 v195, v162
	s_add_i32 s8, s39, s15
	s_mov_b32 m0, s8
	s_nop 0
	global_load_lds_dwordx4 v195, s[4:5]
	v_mov_b32_e32 v195, v190
	s_add_i32 m0, s8, 0x2000
	s_nop 0
	global_load_lds_dwordx4 v195, s[4:5]
	v_mov_b32_e32 v195, v1
	s_mov_b32 m0, s24
	s_nop 0
	global_load_lds_dwordx4 v195, s[6:7]
	v_mov_b32_e32 v195, v164
	s_mov_b32 m0, s25
	s_nop 0
	global_load_lds_dwordx4 v195, s[6:7]
	s_waitcnt vmcnt(8)
	s_waitcnt lgkmcnt(0)
	s_barrier
	s_setprio 1
	s_waitcnt lgkmcnt(0)
	v_mfma_f32_16x16x32_bf16 v[110:113], v[74:77], v[178:181], v[110:113]
	v_mfma_f32_16x16x32_bf16 v[94:97], v[74:77], v[186:189], v[94:97]
	v_mfma_f32_16x16x32_bf16 v[86:89], v[74:77], v[200:203], v[86:89]
	v_mfma_f32_16x16x32_bf16 v[34:37], v[74:77], v[208:211], v[34:37]
	v_mfma_f32_16x16x32_bf16 v[110:113], v[78:81], v[182:185], v[110:113]
	v_mfma_f32_16x16x32_bf16 v[106:109], v[98:101], v[178:181], v[106:109]
	v_mfma_f32_16x16x32_bf16 v[94:97], v[78:81], v[196:199], v[94:97]
	v_mfma_f32_16x16x32_bf16 v[90:93], v[98:101], v[186:189], v[90:93]
	v_mfma_f32_16x16x32_bf16 v[86:89], v[78:81], v[204:207], v[86:89]
	v_mfma_f32_16x16x32_bf16 v[82:85], v[98:101], v[200:203], v[82:85]
	v_mfma_f32_16x16x32_bf16 v[78:81], v[78:81], v[212:215], v[34:37]
	v_mfma_f32_16x16x32_bf16 v[34:37], v[98:101], v[208:211], v[38:41]
	v_mfma_f32_16x16x32_bf16 v[106:109], v[102:105], v[182:185], v[106:109]
	v_mfma_f32_16x16x32_bf16 v[90:93], v[102:105], v[196:199], v[90:93]
	v_mfma_f32_16x16x32_bf16 v[82:85], v[102:105], v[204:207], v[82:85]
	v_mfma_f32_16x16x32_bf16 v[74:77], v[102:105], v[212:215], v[34:37]
	s_setprio 0
	s_setprio 1
	v_mfma_f32_16x16x32_bf16 v[30:33], v[146:149], v[178:181], v[30:33]
	v_mfma_f32_16x16x32_bf16 v[30:33], v[150:153], v[182:185], v[30:33]
	v_mfma_f32_16x16x32_bf16 v[22:25], v[146:149], v[186:189], v[22:25]
	v_mfma_f32_16x16x32_bf16 v[22:25], v[150:153], v[196:199], v[22:25]
	v_mfma_f32_16x16x32_bf16 v[14:17], v[146:149], v[200:203], v[14:17]
	v_mfma_f32_16x16x32_bf16 v[14:17], v[150:153], v[204:207], v[14:17]
	v_mfma_f32_16x16x32_bf16 v[6:9], v[146:149], v[208:211], v[6:9]
	v_mfma_f32_16x16x32_bf16 v[6:9], v[150:153], v[212:215], v[6:9]
	v_mfma_f32_16x16x32_bf16 v[26:29], v[154:157], v[178:181], v[26:29]
	v_mfma_f32_16x16x32_bf16 v[26:29], v[158:161], v[182:185], v[26:29]
	v_mfma_f32_16x16x32_bf16 v[18:21], v[154:157], v[186:189], v[18:21]
	v_mfma_f32_16x16x32_bf16 v[18:21], v[158:161], v[196:199], v[18:21]
	v_mfma_f32_16x16x32_bf16 v[10:13], v[154:157], v[200:203], v[10:13]
	v_mfma_f32_16x16x32_bf16 v[10:13], v[158:161], v[204:207], v[10:13]
	v_mfma_f32_16x16x32_bf16 v[2:5], v[154:157], v[208:211], v[2:5]
	v_mfma_f32_16x16x32_bf16 v[2:5], v[158:161], v[212:215], v[2:5]
	s_setprio 0
	s_barrier
	s_add_i32 s35, s35, 2
	s_add_u32 s31, s31, 0x100
	s_addc_u32 s34, s34, 0
	s_cmpk_gt_u32 s35, 0x55
	s_mov_b64 s[4:5], s[2:3]
	s_cbranch_scc0 .LBB0_707
	s_ashr_i32 s2, s29, 31
	s_lshr_b32 s2, s2, 27
	s_add_i32 s2, s29, s2
	s_ashr_i32 s2, s2, 5
	v_lshl_or_b32 v156, s30, 8, v193
	s_mul_i32 s5, s2, 0xc000
	v_ashrrev_i32_e32 v157, 31, v156
	s_mul_hi_i32 s4, s2, 0xc000
	s_add_u32 s2, s20, s5
	s_addc_u32 s3, s21, s4
	v_lshlrev_b64 v[34:35], 2, v[156:157]
	v_lshl_add_u64 v[38:39], s[2:3], 0, v[34:35]
	global_load_dwordx4 v[98:101], v[38:39], off offset:16
	global_load_dwordx4 v[102:105], v[38:39], off
	s_add_u32 s2, s22, s5
	s_addc_u32 s3, s23, s4
	v_lshl_add_u64 v[148:149], s[2:3], 0, v[34:35]
	v_lshl_add_u64 v[146:147], s[48:49], 0, v[34:35]
	v_mov_b32_e32 v158, 0
	v_cndmask_b32_e64 v34, 0, 1, s[46:47]
	v_cmp_ne_u32_e64 s[2:3], 1, v34
	s_andn2_b64 vcc, exec, s[46:47]
	v_mov_b32_e32 v159, v158
	v_mov_b32_e32 v160, v158
	v_mov_b32_e32 v161, v158
	v_mov_b32_e32 v178, v158
	v_mov_b32_e32 v179, v158
	v_mov_b32_e32 v180, v158
	v_mov_b32_e32 v181, v158
	s_cbranch_vccnz .LBB0_710
	global_load_dwordx4 v[34:37], v[148:149], off
	global_load_dwordx4 v[150:153], v[148:149], off offset:16
	global_load_dwordx4 v[158:161], v[146:147], off
	global_load_dwordx4 v[178:181], v[146:147], off offset:16
	s_waitcnt vmcnt(0)
	v_pk_add_f32 v[36:37], v[36:37], 1.0 op_sel_hi:[1,0]
	v_pk_add_f32 v[34:35], v[34:35], 1.0 op_sel_hi:[1,0]
	v_pk_add_f32 v[40:41], v[152:153], 1.0 op_sel_hi:[1,0]
	v_pk_add_f32 v[150:151], v[150:151], 1.0 op_sel_hi:[1,0]
	v_pk_mul_f32 v[160:161], v[160:161], v[36:37]
	v_pk_mul_f32 v[158:159], v[158:159], v[34:35]
	v_pk_mul_f32 v[180:181], v[180:181], v[40:41]
	v_pk_mul_f32 v[178:179], v[178:179], v[150:151]
